# q_tile / kv_tile epilogues: gain-vector loads software-pipelined through a 3-quad ring with counted vmcnt (no store-ack wait per step)
# baseline (speedup 1.0000x reference)
; #define MFMA(a, b, c) __builtin_amdgcn_mfma_f32_32x32x16_bf16((a), (b), (c), 0, 0, 0)
; DI int fresh_tid(const Params& p) { int t = p.wave_u * 64 + (int)__builtin_amdgcn_mbcnt_hi(~0u, __builtin_amdgcn_mbcnt_lo(~0u, 0u)); asm volatile("" : "+v"(t)); return t; }
; template <int BM, int BN, int BK, int WAVES_M, int WAVES_N, int UNSWAP_FROM>
; DI void gemm_mainloop(const int tid, const bf16_t* __restrict__ A, int lda, const bf16_t* __restrict__ Bt, int ldb, int K, unsigned char* smem,
;                       f32x16 (&acc)[BM / WAVES_M / 32][BN / WAVES_N / 32]) {
;     ...
;     const int nk = K / BK;
;     ...
;     G_LOAD(0); G_STORE(0); __syncthreads();
;     for (int kt = 0; kt < nk; ++kt) {
;         const int buf = kt & 1;
;         if (kt + 1 < nk) G_LOAD(kt + 1);
;         const unsigned char* sa_ = smem + buf * STAGE; const unsigned char* sb_ = sa_ + A_ST;
; #pragma unroll
;         for (int ks = 0; ks < BK / 16; ++ks) {
;             bf16x8 af[WM], bfr[WN];
; #pragma unroll
;             for (int i = 0; i < WM; ++i) af[i] = *(const bf16x8*)(sa_ + (((wm * WM + i) * 32 + r) * LS + ks * 16 + h * 8) * 2);
; #pragma unroll
;             for (int j = 0; j < WN; ++j) bfr[j] = *(const bf16x8*)(sb_ + (((wn * WN + j) * 32 + r) * LS + ks * 16 + h * 8) * 2);
; #pragma unroll
;             for (int i = 0; i < WM; ++i)
; #pragma unroll
;                 for (int j = 0; j < WN; ++j) {
;                     if (j < UNSWAP_FROM) acc[i][j] = MFMA(bfr[j], af[i], acc[i][j]);
;                     else acc[i][j] = MFMA(af[i], bfr[j], acc[i][j]);
;                 }
;         }
;         if (kt + 1 < nk) G_STORE(buf ^ 1);
;         __syncthreads();
; DI void kv_tile(const Params& p, int mt, int hd, unsigned char* smem) {
;     const bf16_t* pa = (const bf16_t*)(p.ws + WS_PA);
;     const bf16_t* wt = (const bf16_t*)(p.ws + WS_WUKV);
;     const float* ssq = (const float*)(p.ws + WS_SSQ) + T_;
;     bf16_t* Kb = (bf16_t*)(p.ws + WS_K); bf16_t* Vt = (bf16_t*)(p.ws + WS_VT);
;     const int tid = fresh_tid(p), lane = tid & 63, wave = tid >> 6, r = lane & 31, h = lane >> 5;
;     f32x16 acc[1][4];
;     const int mw = mt * 128 + wave * 32;
;     const int bb = mw >> 13, sw = mw & 8191, bh = bb * 8 + hd;
;     gemm_mainloop<128, 128, 32, 4, 1, 0>(tid, pa + (size_t)mt * 128 * LDPA + 512, LDPA, wt + (size_t)(hd * 256 + 128) * 256, 256, 256, smem, acc);
.LBB0_158:
	s_cmpk_gt_i32 s51, 0xfff
	s_mov_b64 s[4:5], -1
	s_cbranch_scc0 .LBB0_164
	s_and_b32 s15, s51, 7
	s_cmpk_gt_u32 s51, 0x17ff
	s_cbranch_scc0 .LBB0_161
	v_mov_b32_e32 v79, v227
	s_add_i32 s4, s51, 0xffffe800
	s_lshr_b32 s4, s4, 3
	v_ashrrev_i32_e32 v0, 1, v79
	v_and_b32_e32 v0, 0xffffffe0, v0
	v_lshl_add_u32 v64, s4, 7, v0
	v_ashrrev_i32_e32 v0, 31, v79
	s_mul_i32 s44, s4, 0x5c000
	v_lshrrev_b32_e32 v0, 30, v0
	s_lshl_b64 s[4:5], s[44:45], 1
	v_add_u32_e32 v0, v79, v0
	s_add_u32 s4, s8, s4
	v_ashrrev_i32_e32 v16, 2, v0
	v_and_b32_e32 v0, -4, v0
	s_addc_u32 s5, s9, s5
	s_lshl_b32 s44, s15, 17
	v_readlane_b32 s74, v244, 25
	v_sub_u32_e32 v20, v79, v0
	s_add_u32 s74, s74, s44
	v_readlane_b32 s44, v244, 26
	v_lshlrev_b32_e32 v2, 3, v20
	v_add_u32_e32 v6, 0x100, v79
	s_addc_u32 s75, s44, 0
	v_mov_b64_e32 v[4:5], s[4:5]
	s_movk_i32 s44, 0x1700
	v_ashrrev_i32_e32 v3, 31, v2
	v_ashrrev_i32_e32 v7, 31, v6
	v_mad_i64_i32 v[0:1], s[4:5], v16, s44, v[4:5]
	v_lshlrev_b64 v[72:73], 1, v[2:3]
	v_lshrrev_b32_e32 v7, 30, v7
	v_lshl_add_u64 v[66:67], v[0:1], 0, v[72:73]
	v_add_u32_e32 v7, v6, v7
	global_load_dwordx4 v[0:3], v[66:67], off offset:1024
	v_ashrrev_i32_e32 v18, 2, v7
	v_and_b32_e32 v7, -4, v7
	v_sub_u32_e32 v21, v6, v7
	v_lshlrev_b32_e32 v6, 3, v21
	s_add_u32 s76, s74, 0x10000
	v_ashrrev_i32_e32 v17, 31, v16
	v_ashrrev_i32_e32 v7, 31, v6
	s_addc_u32 s77, s75, 0
	v_ashrrev_i32_e32 v19, 31, v18
	v_mad_i64_i32 v[4:5], s[4:5], v18, s44, v[4:5]
	v_lshlrev_b64 v[70:71], 1, v[6:7]
	v_lshlrev_b64 v[76:77], 9, v[16:17]
	v_lshl_add_u64 v[68:69], v[4:5], 0, v[70:71]
	v_lshl_add_u64 v[8:9], s[76:77], 0, v[76:77]
	v_lshlrev_b64 v[74:75], 9, v[18:19]
	global_load_dwordx4 v[4:7], v[68:69], off offset:1024
	v_lshl_add_u64 v[8:9], v[8:9], 0, v[72:73]
	v_lshl_add_u64 v[12:13], s[76:77], 0, v[74:75]
	global_load_dwordx4 v[8:11], v[8:9], off
	v_lshl_add_u64 v[12:13], v[12:13], 0, v[70:71]
	global_load_dwordx4 v[12:15], v[12:13], off
	s_movk_i32 s4, 0x50
	v_lshlrev_b32_e32 v17, 4, v20
	v_mul_lo_u32 v16, v16, s4
	v_add3_u32 v93, v17, v16, s10
	v_and_b32_e32 v92, 31, v79
	s_mov_b32 s5, 0xfffffe0
	v_ashrrev_i32_e32 v65, 10, v64
	v_readlane_b32 s76, v244, 27
	v_and_or_b32 v78, v65, -8, s15
	v_ashrrev_i32_e32 v65, 31, v64
	v_readlane_b32 s77, v244, 28
	v_and_b32_e32 v97, 0x1fe0, v64
	s_waitcnt vmcnt(3)
	ds_write_b128 v93, v[0:3]
	v_lshlrev_b32_e32 v0, 4, v21
	v_mul_lo_u32 v1, v18, s4
	v_add3_u32 v94, v0, v1, s10
	v_lshrrev_b32_e32 v0, 1, v79
	v_and_or_b32 v1, v0, s5, v92
	v_mul_lo_u32 v3, v1, s4
	s_add_u32 s4, s74, 0x10040
	s_addc_u32 s5, s75, 0
	v_and_b32_e32 v2, 16, v0
	v_lshl_add_u64 v[0:1], s[4:5], 0, v[76:77]
	s_waitcnt vmcnt(2)
	ds_write_b128 v94, v[4:7]
	s_waitcnt vmcnt(1)
	ds_write_b128 v93, v[8:11] offset:10240
	s_waitcnt vmcnt(0)
	ds_write_b128 v94, v[12:15] offset:10240
	s_waitcnt lgkmcnt(0)
	s_barrier
	global_load_dwordx4 v[80:83], v[66:67], off offset:1088
	global_load_dwordx4 v[84:87], v[68:69], off offset:1088
	v_lshl_add_u64 v[0:1], v[0:1], 0, v[72:73]
	global_load_dwordx4 v[88:91], v[0:1], off
	v_lshl_add_u64 v[0:1], s[4:5], 0, v[74:75]
	v_lshl_add_u64 v[0:1], v[0:1], 0, v[70:71]
	global_load_dwordx4 v[98:101], v[0:1], off
	v_mul_u32_u24_e32 v4, 0x50, v92
	s_add_u32 s4, s74, 0x10080
	v_add3_u32 v95, v2, v4, s10
	s_addc_u32 s5, s75, 0
	v_add3_u32 v96, v3, v2, s10
	ds_read_b128 v[0:3], v95 offset:12800
	ds_read_b128 v[4:7], v95 offset:15360
	ds_read_b128 v[8:11], v95 offset:17920
	ds_read_b128 v[12:15], v96
	ds_read_b128 v[102:105], v96 offset:32
	ds_read_b128 v[16:19], v95 offset:10240
	ds_read_b128 v[106:109], v95 offset:10272
	ds_read_b128 v[110:113], v95 offset:12832
	ds_read_b128 v[120:123], v95 offset:15392
	ds_read_b128 v[124:127], v95 offset:17952
	s_waitcnt lgkmcnt(4)
	v_mfma_f32_32x32x16_bf16 v[48:63], v[12:15], v[16:19], 0
	s_waitcnt vmcnt(3)
	ds_write_b128 v93, v[80:83] offset:20480
	s_waitcnt vmcnt(2)
	ds_write_b128 v94, v[84:87] offset:20480
	s_waitcnt vmcnt(1)
	ds_write_b128 v93, v[88:91] offset:30720
	s_waitcnt vmcnt(0)
	ds_write_b128 v94, v[98:101] offset:30720
	s_waitcnt lgkmcnt(0)
	s_barrier
	global_load_dwordx4 v[80:83], v[66:67], off offset:1152
	global_load_dwordx4 v[84:87], v[68:69], off offset:1152
	v_lshl_add_u64 v[88:89], s[4:5], 0, v[76:77]
	v_lshl_add_u64 v[88:89], v[88:89], 0, v[72:73]
	v_lshl_add_u64 v[98:99], s[4:5], 0, v[74:75]
	global_load_dwordx4 v[88:91], v[88:89], off
	v_lshl_add_u64 v[98:99], v[98:99], 0, v[70:71]
	global_load_dwordx4 v[98:101], v[98:99], off
	v_mfma_f32_32x32x16_bf16 v[32:47], v[12:15], v[0:3], 0
	s_add_u32 s4, s74, 0x100c0
	s_addc_u32 s5, s75, 0
	v_mfma_f32_32x32x16_bf16 v[16:31], v[12:15], v[4:7], 0
	v_mfma_f32_32x32x16_bf16 v[0:15], v[12:15], v[8:11], 0
	v_mfma_f32_32x32x16_bf16 v[32:47], v[102:105], v[110:113], v[32:47]
	v_mfma_f32_32x32x16_bf16 v[16:31], v[102:105], v[120:123], v[16:31]
	v_mfma_f32_32x32x16_bf16 v[0:15], v[102:105], v[124:127], v[0:15]
	v_mfma_f32_32x32x16_bf16 v[48:63], v[102:105], v[106:109], v[48:63]
	ds_read_b128 v[102:105], v95 offset:33280
	ds_read_b128 v[106:109], v95 offset:35840
	ds_read_b128 v[110:113], v95 offset:38400
	ds_read_b128 v[120:123], v96 offset:20480
	ds_read_b128 v[124:127], v96 offset:20512
	ds_read_b128 v[128:131], v95 offset:30720
	ds_read_b128 v[132:135], v95 offset:30752
	s_waitcnt lgkmcnt(3)
	v_mfma_f32_32x32x16_bf16 v[32:47], v[120:123], v[102:105], v[32:47]
	v_mfma_f32_32x32x16_bf16 v[16:31], v[120:123], v[106:109], v[16:31]
	v_mfma_f32_32x32x16_bf16 v[0:15], v[120:123], v[110:113], v[0:15]
	ds_read_b128 v[102:105], v95 offset:33312
	ds_read_b128 v[106:109], v95 offset:35872
	ds_read_b128 v[110:113], v95 offset:38432
	s_waitcnt vmcnt(3)
	ds_write_b128 v93, v[80:83]
	s_waitcnt vmcnt(2)
	ds_write_b128 v94, v[84:87]
	s_waitcnt vmcnt(1)
	ds_write_b128 v93, v[88:91] offset:10240
	s_waitcnt vmcnt(0)
	ds_write_b128 v94, v[98:101] offset:10240
	s_waitcnt lgkmcnt(0)
	s_barrier
; #define MFMA(a, b, c) __builtin_amdgcn_mfma_f32_32x32x16_bf16((a), (b), (c), 0, 0, 0)
; template <int BM, int BN, int BK, int WAVES_M, int WAVES_N, int UNSWAP_FROM>
; DI void gemm_mainloop(const int tid, const bf16_t* __restrict__ A, int lda, const bf16_t* __restrict__ Bt, int ldb, int K, unsigned char* smem,
;                       f32x16 (&acc)[BM / WAVES_M / 32][BN / WAVES_N / 32]) {
;     ...
;     for (int kt = 0; kt < nk; ++kt) {
;         const int buf = kt & 1;
;         if (kt + 1 < nk) G_LOAD(kt + 1);
;         const unsigned char* sa_ = smem + buf * STAGE; const unsigned char* sb_ = sa_ + A_ST;
; #pragma unroll
;         for (int ks = 0; ks < BK / 16; ++ks) {
;             bf16x8 af[WM], bfr[WN];
; #pragma unroll
;             for (int i = 0; i < WM; ++i) af[i] = *(const bf16x8*)(sa_ + (((wm * WM + i) * 32 + r) * LS + ks * 16 + h * 8) * 2);
; #pragma unroll
;             for (int j = 0; j < WN; ++j) bfr[j] = *(const bf16x8*)(sb_ + (((wn * WN + j) * 32 + r) * LS + ks * 16 + h * 8) * 2);
; #pragma unroll
;             for (int i = 0; i < WM; ++i)
; #pragma unroll
;                 for (int j = 0; j < WN; ++j) {
;                     if (j < UNSWAP_FROM) acc[i][j] = MFMA(bfr[j], af[i], acc[i][j]);
;                     else acc[i][j] = MFMA(af[i], bfr[j], acc[i][j]);
;                 }
;         }
;         if (kt + 1 < nk) G_STORE(buf ^ 1);
;         __syncthreads();
	global_load_dwordx4 v[80:83], v[66:67], off offset:1216
	global_load_dwordx4 v[84:87], v[68:69], off offset:1216
	v_lshl_add_u64 v[88:89], s[4:5], 0, v[76:77]
	v_lshl_add_u64 v[88:89], v[88:89], 0, v[72:73]
	v_lshl_add_u64 v[98:99], s[4:5], 0, v[74:75]
	global_load_dwordx4 v[88:91], v[88:89], off
	v_lshl_add_u64 v[98:99], v[98:99], 0, v[70:71]
	global_load_dwordx4 v[98:101], v[98:99], off
	v_mfma_f32_32x32x16_bf16 v[48:63], v[120:123], v[128:131], v[48:63]
	s_add_u32 s4, s74, 0x10100
	s_addc_u32 s5, s75, 0
	v_mfma_f32_32x32x16_bf16 v[32:47], v[124:127], v[102:105], v[32:47]
	v_mfma_f32_32x32x16_bf16 v[16:31], v[124:127], v[106:109], v[16:31]
	v_mfma_f32_32x32x16_bf16 v[0:15], v[124:127], v[110:113], v[0:15]
	v_mfma_f32_32x32x16_bf16 v[48:63], v[124:127], v[132:135], v[48:63]
	ds_read_b128 v[102:105], v95 offset:12800
	ds_read_b128 v[106:109], v95 offset:15360
	ds_read_b128 v[110:113], v95 offset:17920
	ds_read_b128 v[120:123], v96
	ds_read_b128 v[124:127], v96 offset:32
	ds_read_b128 v[128:131], v95 offset:10240
	ds_read_b128 v[132:135], v95 offset:10272
	s_waitcnt lgkmcnt(3)
	v_mfma_f32_32x32x16_bf16 v[32:47], v[120:123], v[102:105], v[32:47]
	v_mfma_f32_32x32x16_bf16 v[16:31], v[120:123], v[106:109], v[16:31]
	v_mfma_f32_32x32x16_bf16 v[0:15], v[120:123], v[110:113], v[0:15]
	ds_read_b128 v[102:105], v95 offset:12832
	ds_read_b128 v[106:109], v95 offset:15392
	ds_read_b128 v[110:113], v95 offset:17952
	s_waitcnt vmcnt(3)
	ds_write_b128 v93, v[80:83] offset:20480
	s_waitcnt vmcnt(2)
	ds_write_b128 v94, v[84:87] offset:20480
	s_waitcnt vmcnt(1)
	ds_write_b128 v93, v[88:91] offset:30720
	s_waitcnt vmcnt(0)
	ds_write_b128 v94, v[98:101] offset:30720
	s_waitcnt lgkmcnt(0)
	s_barrier
	global_load_dwordx4 v[80:83], v[66:67], off offset:1280
	global_load_dwordx4 v[84:87], v[68:69], off offset:1280
	v_lshl_add_u64 v[88:89], s[4:5], 0, v[76:77]
	v_lshl_add_u64 v[88:89], v[88:89], 0, v[72:73]
	v_lshl_add_u64 v[98:99], s[4:5], 0, v[74:75]
	global_load_dwordx4 v[88:91], v[88:89], off
	v_lshl_add_u64 v[98:99], v[98:99], 0, v[70:71]
	global_load_dwordx4 v[98:101], v[98:99], off
	v_mfma_f32_32x32x16_bf16 v[48:63], v[120:123], v[128:131], v[48:63]
	s_add_u32 s4, s74, 0x10140
	s_addc_u32 s5, s75, 0
	v_mfma_f32_32x32x16_bf16 v[32:47], v[124:127], v[102:105], v[32:47]
	v_mfma_f32_32x32x16_bf16 v[16:31], v[124:127], v[106:109], v[16:31]
	v_mfma_f32_32x32x16_bf16 v[0:15], v[124:127], v[110:113], v[0:15]
	v_mfma_f32_32x32x16_bf16 v[48:63], v[124:127], v[132:135], v[48:63]
	ds_read_b128 v[102:105], v95 offset:33280
	ds_read_b128 v[106:109], v95 offset:35840
	ds_read_b128 v[110:113], v95 offset:38400
	ds_read_b128 v[120:123], v96 offset:20480
	ds_read_b128 v[124:127], v96 offset:20512
	ds_read_b128 v[128:131], v95 offset:30720
	ds_read_b128 v[132:135], v95 offset:30752
	s_waitcnt lgkmcnt(3)
	v_mfma_f32_32x32x16_bf16 v[32:47], v[120:123], v[102:105], v[32:47]
	v_mfma_f32_32x32x16_bf16 v[16:31], v[120:123], v[106:109], v[16:31]
	v_mfma_f32_32x32x16_bf16 v[0:15], v[120:123], v[110:113], v[0:15]
	ds_read_b128 v[102:105], v95 offset:33312
	ds_read_b128 v[106:109], v95 offset:35872
	ds_read_b128 v[110:113], v95 offset:38432
	s_waitcnt vmcnt(3)
	ds_write_b128 v93, v[80:83]
	s_waitcnt vmcnt(2)
	ds_write_b128 v94, v[84:87]
	s_waitcnt vmcnt(1)
	ds_write_b128 v93, v[88:91] offset:10240
	s_waitcnt vmcnt(0)
	ds_write_b128 v94, v[98:101] offset:10240
	s_waitcnt lgkmcnt(0)
	s_barrier
	global_load_dwordx4 v[80:83], v[66:67], off offset:1344
	global_load_dwordx4 v[84:87], v[68:69], off offset:1344
	v_lshl_add_u64 v[88:89], s[4:5], 0, v[76:77]
	v_lshl_add_u64 v[88:89], v[88:89], 0, v[72:73]
	v_lshl_add_u64 v[98:99], s[4:5], 0, v[74:75]
	global_load_dwordx4 v[88:91], v[88:89], off
	v_lshl_add_u64 v[98:99], v[98:99], 0, v[70:71]
	global_load_dwordx4 v[98:101], v[98:99], off
	v_mfma_f32_32x32x16_bf16 v[48:63], v[120:123], v[128:131], v[48:63]
	s_add_u32 s4, s74, 0x10180
	s_addc_u32 s5, s75, 0
	v_mfma_f32_32x32x16_bf16 v[32:47], v[124:127], v[102:105], v[32:47]
	v_mfma_f32_32x32x16_bf16 v[16:31], v[124:127], v[106:109], v[16:31]
	v_mfma_f32_32x32x16_bf16 v[0:15], v[124:127], v[110:113], v[0:15]
	v_mfma_f32_32x32x16_bf16 v[48:63], v[124:127], v[132:135], v[48:63]
	ds_read_b128 v[102:105], v95 offset:12800
	ds_read_b128 v[106:109], v95 offset:15360
	ds_read_b128 v[110:113], v95 offset:17920
	ds_read_b128 v[120:123], v96
	ds_read_b128 v[124:127], v96 offset:32
	ds_read_b128 v[128:131], v95 offset:10240
	ds_read_b128 v[132:135], v95 offset:10272
	s_waitcnt lgkmcnt(3)
	v_mfma_f32_32x32x16_bf16 v[32:47], v[120:123], v[102:105], v[32:47]
	v_mfma_f32_32x32x16_bf16 v[16:31], v[120:123], v[106:109], v[16:31]
	v_mfma_f32_32x32x16_bf16 v[0:15], v[120:123], v[110:113], v[0:15]
	ds_read_b128 v[102:105], v95 offset:12832
	ds_read_b128 v[106:109], v95 offset:15392
	ds_read_b128 v[110:113], v95 offset:17952
	s_waitcnt vmcnt(3)
	ds_write_b128 v93, v[80:83] offset:20480
	s_waitcnt vmcnt(2)
	ds_write_b128 v94, v[84:87] offset:20480
	s_waitcnt vmcnt(1)
	ds_write_b128 v93, v[88:91] offset:30720
	s_waitcnt vmcnt(0)
	ds_write_b128 v94, v[98:101] offset:30720
	s_waitcnt lgkmcnt(0)
	s_barrier
; #define MFMA(a, b, c) __builtin_amdgcn_mfma_f32_32x32x16_bf16((a), (b), (c), 0, 0, 0)
; template <int BM, int BN, int BK, int WAVES_M, int WAVES_N, int UNSWAP_FROM>
; DI void gemm_mainloop(const int tid, const bf16_t* __restrict__ A, int lda, const bf16_t* __restrict__ Bt, int ldb, int K, unsigned char* smem,
;                       f32x16 (&acc)[BM / WAVES_M / 32][BN / WAVES_N / 32]) {
;     ...
;     for (int kt = 0; kt < nk; ++kt) {
;         const int buf = kt & 1;
;         if (kt + 1 < nk) G_LOAD(kt + 1);
;         const unsigned char* sa_ = smem + buf * STAGE; const unsigned char* sb_ = sa_ + A_ST;
; #pragma unroll
;         for (int ks = 0; ks < BK / 16; ++ks) {
;             bf16x8 af[WM], bfr[WN];
; #pragma unroll
;             for (int i = 0; i < WM; ++i) af[i] = *(const bf16x8*)(sa_ + (((wm * WM + i) * 32 + r) * LS + ks * 16 + h * 8) * 2);
; #pragma unroll
;             for (int j = 0; j < WN; ++j) bfr[j] = *(const bf16x8*)(sb_ + (((wn * WN + j) * 32 + r) * LS + ks * 16 + h * 8) * 2);
; #pragma unroll
;             for (int i = 0; i < WM; ++i)
; #pragma unroll
;                 for (int j = 0; j < WN; ++j) {
;                     if (j < UNSWAP_FROM) acc[i][j] = MFMA(bfr[j], af[i], acc[i][j]);
;                     else acc[i][j] = MFMA(af[i], bfr[j], acc[i][j]);
;                 }
;         }
;         if (kt + 1 < nk) G_STORE(buf ^ 1);
;         __syncthreads();
	global_load_dwordx4 v[80:83], v[66:67], off offset:1408
	global_load_dwordx4 v[84:87], v[68:69], off offset:1408
	v_lshl_add_u64 v[88:89], s[4:5], 0, v[76:77]
	v_lshl_add_u64 v[88:89], v[88:89], 0, v[72:73]
	v_lshl_add_u64 v[98:99], s[4:5], 0, v[74:75]
	global_load_dwordx4 v[88:91], v[88:89], off
	v_lshl_add_u64 v[98:99], v[98:99], 0, v[70:71]
	global_load_dwordx4 v[98:101], v[98:99], off
	v_mfma_f32_32x32x16_bf16 v[48:63], v[120:123], v[128:131], v[48:63]
	s_add_u32 s4, s74, 0x101c0
	s_addc_u32 s5, s75, 0
	v_mfma_f32_32x32x16_bf16 v[32:47], v[124:127], v[102:105], v[32:47]
	v_mfma_f32_32x32x16_bf16 v[16:31], v[124:127], v[106:109], v[16:31]
	v_mfma_f32_32x32x16_bf16 v[0:15], v[124:127], v[110:113], v[0:15]
	v_mfma_f32_32x32x16_bf16 v[48:63], v[124:127], v[132:135], v[48:63]
	ds_read_b128 v[102:105], v95 offset:33280
	ds_read_b128 v[106:109], v95 offset:35840
	ds_read_b128 v[110:113], v95 offset:38400
	ds_read_b128 v[120:123], v96 offset:20480
	ds_read_b128 v[124:127], v96 offset:20512
	ds_read_b128 v[128:131], v95 offset:30720
	ds_read_b128 v[132:135], v95 offset:30752
	s_waitcnt lgkmcnt(3)
	v_mfma_f32_32x32x16_bf16 v[32:47], v[120:123], v[102:105], v[32:47]
	v_mfma_f32_32x32x16_bf16 v[16:31], v[120:123], v[106:109], v[16:31]
	v_mfma_f32_32x32x16_bf16 v[0:15], v[120:123], v[110:113], v[0:15]
	ds_read_b128 v[102:105], v95 offset:33312
	ds_read_b128 v[106:109], v95 offset:35872
	ds_read_b128 v[110:113], v95 offset:38432
	s_waitcnt vmcnt(3)
	ds_write_b128 v93, v[80:83]
	s_waitcnt vmcnt(2)
	ds_write_b128 v94, v[84:87]
	s_waitcnt vmcnt(1)
	ds_write_b128 v93, v[88:91] offset:10240
	s_waitcnt vmcnt(0)
	ds_write_b128 v94, v[98:101] offset:10240
	s_waitcnt lgkmcnt(0)
	s_barrier
	global_load_dwordx4 v[80:83], v[66:67], off offset:1472
	global_load_dwordx4 v[84:87], v[68:69], off offset:1472
	v_lshl_add_u64 v[88:89], s[4:5], 0, v[76:77]
	v_lshl_add_u64 v[88:89], v[88:89], 0, v[72:73]
	v_lshl_add_u64 v[98:99], s[4:5], 0, v[74:75]
	global_load_dwordx4 v[88:91], v[88:89], off
	v_lshl_add_u64 v[98:99], v[98:99], 0, v[70:71]
	global_load_dwordx4 v[98:101], v[98:99], off
	v_mfma_f32_32x32x16_bf16 v[48:63], v[120:123], v[128:131], v[48:63]
	v_readlane_b32 s4, v244, 29
	v_readlane_b32 s5, v244, 30
	v_mfma_f32_32x32x16_bf16 v[32:47], v[124:127], v[102:105], v[32:47]
	v_mfma_f32_32x32x16_bf16 v[0:15], v[124:127], v[110:113], v[0:15]
	v_mfma_f32_32x32x16_bf16 v[16:31], v[124:127], v[106:109], v[16:31]
	v_mfma_f32_32x32x16_bf16 v[48:63], v[124:127], v[132:135], v[48:63]
	ds_read_b128 v[102:105], v95 offset:12800
	ds_read_b128 v[106:109], v95 offset:15360
	ds_read_b128 v[110:113], v95 offset:17920
	ds_read_b128 v[120:123], v96
	ds_read_b128 v[124:127], v96 offset:32
	ds_read_b128 v[128:131], v95 offset:10240
	ds_read_b128 v[132:135], v95 offset:10272
	s_waitcnt lgkmcnt(3)
	v_mfma_f32_32x32x16_bf16 v[32:47], v[120:123], v[102:105], v[32:47]
	v_mfma_f32_32x32x16_bf16 v[0:15], v[120:123], v[110:113], v[0:15]
	v_mfma_f32_32x32x16_bf16 v[16:31], v[120:123], v[106:109], v[16:31]
	ds_read_b128 v[102:105], v95 offset:12832
	ds_read_b128 v[106:109], v95 offset:15392
	ds_read_b128 v[110:113], v95 offset:17952
	s_waitcnt vmcnt(3)
	ds_write_b128 v93, v[80:83] offset:20480
	s_waitcnt vmcnt(2)
	ds_write_b128 v94, v[84:87] offset:20480
	s_waitcnt vmcnt(1)
	ds_write_b128 v93, v[88:91] offset:30720
	s_waitcnt vmcnt(0)
	ds_write_b128 v94, v[98:101] offset:30720
	s_waitcnt lgkmcnt(6)
	v_mfma_f32_32x32x16_bf16 v[32:47], v[124:127], v[102:105], v[32:47]
	s_waitcnt lgkmcnt(0)
	s_barrier
	v_mfma_f32_32x32x16_bf16 v[0:15], v[124:127], v[110:113], v[0:15]
	v_mfma_f32_32x32x16_bf16 v[16:31], v[124:127], v[106:109], v[16:31]
	ds_read_b128 v[80:83], v95 offset:33280
	ds_read_b128 v[84:87], v95 offset:35840
	ds_read_b128 v[88:91], v95 offset:38400
	ds_read_b128 v[98:101], v96 offset:20480
	ds_read_b128 v[102:105], v96 offset:20512
	ds_read_b128 v[106:109], v95 offset:30720
	ds_read_b128 v[110:113], v95 offset:30752
	s_waitcnt lgkmcnt(3)
	v_mfma_f32_32x32x16_bf16 v[32:47], v[98:101], v[80:83], v[32:47]
	v_mfma_f32_32x32x16_bf16 v[0:15], v[98:101], v[88:91], v[0:15]
	v_mfma_f32_32x32x16_bf16 v[16:31], v[98:101], v[84:87], v[16:31]
	ds_read_b128 v[80:83], v95 offset:33312
	ds_read_b128 v[84:87], v95 offset:35872
	ds_read_b128 v[88:91], v95 offset:38432
	s_waitcnt lgkmcnt(0)
	s_barrier
; #define MFMA(a, b, c) __builtin_amdgcn_mfma_f32_32x32x16_bf16((a), (b), (c), 0, 0, 0)
; DI unsigned pk2(float a, float b) { f2_t v = {a, b}; bf2_t r = __builtin_convertvector(v, bf2_t); return __builtin_bit_cast(unsigned, r); }
; template <int BM, int BN, int BK, int WAVES_M, int WAVES_N, int UNSWAP_FROM>
; DI void gemm_mainloop(const int tid, const bf16_t* __restrict__ A, int lda, const bf16_t* __restrict__ Bt, int ldb, int K, unsigned char* smem,
;                       f32x16 (&acc)[BM / WAVES_M / 32][BN / WAVES_N / 32]) {
;     ...
;     for (int kt = 0; kt < nk; ++kt) {
;         const int buf = kt & 1;
;         if (kt + 1 < nk) G_LOAD(kt + 1);
;         const unsigned char* sa_ = smem + buf * STAGE; const unsigned char* sb_ = sa_ + A_ST;
; #pragma unroll
;         for (int ks = 0; ks < BK / 16; ++ks) {
;             bf16x8 af[WM], bfr[WN];
; #pragma unroll
;             for (int i = 0; i < WM; ++i) af[i] = *(const bf16x8*)(sa_ + (((wm * WM + i) * 32 + r) * LS + ks * 16 + h * 8) * 2);
; #pragma unroll
;             for (int j = 0; j < WN; ++j) bfr[j] = *(const bf16x8*)(sb_ + (((wn * WN + j) * 32 + r) * LS + ks * 16 + h * 8) * 2);
; #pragma unroll
;             for (int i = 0; i < WM; ++i)
; #pragma unroll
;                 for (int j = 0; j < WN; ++j) {
;                     if (j < UNSWAP_FROM) acc[i][j] = MFMA(bfr[j], af[i], acc[i][j]);
;                     else acc[i][j] = MFMA(af[i], bfr[j], acc[i][j]);
;                 }
;         }
;         if (kt + 1 < nk) G_STORE(buf ^ 1);
;         __syncthreads();
; DI void kv_tile(const Params& p, int mt, int hd, unsigned char* smem) {
;     ...
; #pragma unroll
;     for (int g = 0; g < 4; ++g) {
;         const f32x4 q4 = *(const f32x4*)(ssq + mw + 8 * g + 4 * h);
;         const float r0 = rsqrtf(q4.x * (1.f / 256.f) + EPS), r1 = rsqrtf(q4.y * (1.f / 256.f) + EPS);
;         const float r2 = rsqrtf(q4.z * (1.f / 256.f) + EPS), r3 = rsqrtf(q4.w * (1.f / 256.f) + EPS);
; #pragma unroll
;         for (int j = 0; j < 4; ++j) {
;             u32x2 o; o.x = pk2(acc[0][j][4 * g] * r0, acc[0][j][4 * g + 1] * r1); o.y = pk2(acc[0][j][4 * g + 2] * r2, acc[0][j][4 * g + 3] * r3);
;             *(u32x2*)(Vt + ((size_t)bh * 128 + j * 32 + r) * SEQ_ + sw + 8 * g + 4 * h) = o;
;         }
;     }
	v_mfma_f32_32x32x16_bf16 v[32:47], v[102:105], v[80:83], v[32:47]
	v_lshl_add_u64 v[80:81], v[64:65], 2, s[76:77]
	v_lshrrev_b32_e32 v65, 3, v79
	v_and_b32_e32 v65, 4, v65
	v_lshlrev_b32_e32 v116, 2, v65
	v_lshl_add_u64 v[82:83], v[80:81], 0, v[116:117]
	v_lshlrev_b32_e32 v80, 1, v97
	v_mov_b32_e32 v81, v117
	v_mfma_f32_32x32x16_bf16 v[0:15], v[102:105], v[88:91], v[0:15]
	global_load_dwordx4 v[88:91], v[82:83], off
	v_ashrrev_i32_e32 v79, 31, v78
	v_or_b32_e32 v64, v64, v92
	v_mfma_f32_32x32x16_bf16 v[48:63], v[120:123], v[128:131], v[48:63]
	v_mfma_f32_32x32x16_bf16 v[48:63], v[124:127], v[132:135], v[48:63]
	v_mfma_f32_32x32x16_bf16 v[48:63], v[98:101], v[106:109], v[48:63]
	v_mfma_f32_32x32x16_bf16 v[16:31], v[102:105], v[84:87], v[16:31]
	v_mov_b64_e32 v[86:87], s[48:49]
	v_lshl_add_u64 v[84:85], s[4:5], 0, v[80:81]
	v_lshlrev_b32_e32 v80, 1, v65
	v_lshl_add_u64 v[84:85], v[84:85], 0, v[80:81]
	s_waitcnt vmcnt(0)
	v_pk_fma_f32 v[88:89], v[88:89], s[46:47], v[86:87] op_sel_hi:[1,0,0]
	s_nop 0
	v_mul_f32_e32 v65, 0x4b800000, v88
	v_cmp_gt_f32_e64 s[4:5], s53, v88
	v_mfma_f32_32x32x16_bf16 v[48:63], v[102:105], v[110:113], v[48:63]
	v_cmp_gt_f32_e32 vcc, s53, v89
	v_cndmask_b32_e64 v65, v88, v65, s[4:5]
	v_rsq_f32_e32 v88, v65
	v_mul_f32_e32 v65, 0x4b800000, v89
	v_cndmask_b32_e32 v65, v89, v65, vcc
	v_rsq_f32_e32 v89, v65
	s_nop 0
	v_pk_mul_f32 v[98:99], v[88:89], s[50:51] op_sel_hi:[1,0]
	s_nop 0
	v_cndmask_b32_e32 v89, v89, v99, vcc
	v_cndmask_b32_e64 v88, v88, v98, s[4:5]
	s_nop 0
	v_pk_mul_f32 v[48:49], v[48:49], v[88:89]
	v_pk_mul_f32 v[32:33], v[32:33], v[88:89]
	v_cvt_pk_bf16_f32 v98, v48, v49
	v_pk_fma_f32 v[48:49], v[90:91], s[46:47], v[86:87] op_sel_hi:[1,0,0]
	v_pk_mul_f32 v[16:17], v[16:17], v[88:89]
	v_mul_f32_e32 v65, 0x4b800000, v48
	v_cmp_gt_f32_e64 s[4:5], s53, v48
	v_cmp_gt_f32_e32 vcc, s53, v49
	v_pk_mul_f32 v[0:1], v[0:1], v[88:89]
	v_cndmask_b32_e64 v48, v48, v65, s[4:5]
	v_mul_f32_e32 v65, 0x4b800000, v49
	v_cndmask_b32_e32 v49, v49, v65, vcc
	v_rsq_f32_e32 v48, v48
	v_rsq_f32_e32 v49, v49
	v_cvt_pk_bf16_f32 v0, v0, v1
	v_ashrrev_i32_e32 v65, 31, v64
	v_pk_mul_f32 v[90:91], v[48:49], s[50:51] op_sel_hi:[1,0]
	s_nop 0
	v_cndmask_b32_e32 v91, v49, v91, vcc
	v_cndmask_b32_e64 v90, v48, v90, s[4:5]
	v_pk_mul_f32 v[48:49], v[50:51], v[90:91]
	v_pk_mul_f32 v[2:3], v[2:3], v[90:91]
	v_cvt_pk_bf16_f32 v99, v48, v49
	v_lshlrev_b64 v[48:49], 21, v[78:79]
	v_lshl_or_b32 v48, v92, 14, v48
	v_lshl_add_u64 v[50:51], v[84:85], 0, v[48:49]
	global_store_dwordx2 v[50:51], v[98:99], off
	v_cvt_pk_bf16_f32 v98, v32, v33
	v_pk_mul_f32 v[32:33], v[34:35], v[90:91]
	v_cvt_pk_bf16_f32 v1, v2, v3
	v_cvt_pk_bf16_f32 v99, v32, v33
	v_or_b32_e32 v32, 0x80000, v48
	v_mov_b32_e32 v33, v49
	v_lshl_add_u64 v[34:35], v[84:85], 0, v[32:33]
	global_store_dwordx2 v[34:35], v[98:99], off
	v_cvt_pk_bf16_f32 v34, v16, v17
	v_pk_mul_f32 v[16:17], v[18:19], v[90:91]
	s_nop 0
	v_cvt_pk_bf16_f32 v35, v16, v17
	v_or_b32_e32 v16, 0x100000, v48
	v_mov_b32_e32 v17, v49
	v_or_b32_e32 v48, 0x180000, v48
	v_lshl_add_u64 v[18:19], v[84:85], 0, v[16:17]
	v_lshl_add_u64 v[2:3], v[84:85], 0, v[48:49]
	global_store_dwordx2 v[18:19], v[34:35], off
	global_store_dwordx2 v[2:3], v[0:1], off
	global_load_dwordx4 v[88:91], v[82:83], off offset:32
	v_lshl_add_u64 v[0:1], v[84:85], 0, 16
	s_waitcnt vmcnt(0)
	v_pk_fma_f32 v[2:3], v[88:89], s[46:47], v[86:87] op_sel_hi:[1,0,0]
	s_nop 0
	v_mul_f32_e32 v18, 0x4b800000, v2
	v_cmp_gt_f32_e64 s[4:5], s53, v2
	v_cmp_gt_f32_e32 vcc, s53, v3
	s_nop 0
	v_cndmask_b32_e64 v2, v2, v18, s[4:5]
	v_mul_f32_e32 v18, 0x4b800000, v3
	v_cndmask_b32_e32 v3, v3, v18, vcc
	v_rsq_f32_e32 v2, v2
	v_rsq_f32_e32 v3, v3
	s_nop 0
	v_pk_mul_f32 v[18:19], v[2:3], s[50:51] op_sel_hi:[1,0]
	s_nop 0
	v_cndmask_b32_e32 v3, v3, v19, vcc
	v_cndmask_b32_e64 v2, v2, v18, s[4:5]
	v_pk_mul_f32 v[18:19], v[52:53], v[2:3]
	v_pk_mul_f32 v[20:21], v[20:21], v[2:3]
	v_cvt_pk_bf16_f32 v34, v18, v19
	v_pk_fma_f32 v[18:19], v[90:91], s[46:47], v[86:87] op_sel_hi:[1,0,0]
	v_cvt_pk_bf16_f32 v20, v20, v21
	v_mul_f32_e32 v35, 0x4b800000, v18
	v_cmp_gt_f32_e64 s[4:5], s53, v18
	v_cmp_gt_f32_e32 vcc, s53, v19
	s_nop 0
	v_cndmask_b32_e64 v18, v18, v35, s[4:5]
	v_mul_f32_e32 v35, 0x4b800000, v19
	v_cndmask_b32_e32 v19, v19, v35, vcc
	v_rsq_f32_e32 v18, v18
	v_rsq_f32_e32 v19, v19
	s_nop 0
	v_pk_mul_f32 v[52:53], v[18:19], s[50:51] op_sel_hi:[1,0]
	s_nop 0
	v_cndmask_b32_e32 v19, v19, v53, vcc
	v_cndmask_b32_e64 v18, v18, v52, s[4:5]
	v_pk_mul_f32 v[52:53], v[54:55], v[18:19]
	v_pk_mul_f32 v[22:23], v[22:23], v[18:19]
	v_cvt_pk_bf16_f32 v35, v52, v53
	global_store_dwordx2 v[50:51], v[34:35], off offset:16
	v_pk_mul_f32 v[34:35], v[36:37], v[2:3]
	v_pk_mul_f32 v[36:37], v[38:39], v[18:19]
	v_pk_mul_f32 v[2:3], v[4:5], v[2:3]
	v_pk_mul_f32 v[4:5], v[6:7], v[18:19]
	v_cvt_pk_bf16_f32 v34, v34, v35
	v_cvt_pk_bf16_f32 v35, v36, v37
	v_lshl_add_u64 v[36:37], v[0:1], 0, v[32:33]
	v_cvt_pk_bf16_f32 v21, v22, v23
	v_lshl_add_u64 v[22:23], v[0:1], 0, v[16:17]
	v_cvt_pk_bf16_f32 v2, v2, v3
	v_cvt_pk_bf16_f32 v3, v4, v5
	v_lshl_add_u64 v[0:1], v[0:1], 0, v[48:49]
	global_store_dwordx2 v[36:37], v[34:35], off
	global_store_dwordx2 v[22:23], v[20:21], off
	global_store_dwordx2 v[0:1], v[2:3], off
	global_load_dwordx4 v[2:5], v[82:83], off offset:64
	v_lshl_add_u64 v[0:1], v[84:85], 0, 32
	s_waitcnt vmcnt(0)
; DI unsigned pk2(float a, float b) { f2_t v = {a, b}; bf2_t r = __builtin_convertvector(v, bf2_t); return __builtin_bit_cast(unsigned, r); }
; template <int BM, int BN, int BK, int WAVES_M, int WAVES_N, int UNSWAP_FROM>
; DI void gemm_mainloop(const int tid, const bf16_t* __restrict__ A, int lda, const bf16_t* __restrict__ Bt, int ldb, int K, unsigned char* smem,
;                       f32x16 (&acc)[BM / WAVES_M / 32][BN / WAVES_N / 32]) {
;     ...
;     const int nk = K / BK;
;     ...
;     G_LOAD(0); G_STORE(0); __syncthreads();
; DI void kv_tile(const Params& p, int mt, int hd, unsigned char* smem) {
;     ...
; #pragma unroll
;     for (int g = 0; g < 4; ++g) {
;         const f32x4 q4 = *(const f32x4*)(ssq + mw + 8 * g + 4 * h);
;         const float r0 = rsqrtf(q4.x * (1.f / 256.f) + EPS), r1 = rsqrtf(q4.y * (1.f / 256.f) + EPS);
;         const float r2 = rsqrtf(q4.z * (1.f / 256.f) + EPS), r3 = rsqrtf(q4.w * (1.f / 256.f) + EPS);
; #pragma unroll
;         for (int j = 0; j < 4; ++j) {
;             u32x2 o; o.x = pk2(acc[0][j][4 * g] * r0, acc[0][j][4 * g + 1] * r1); o.y = pk2(acc[0][j][4 * g + 2] * r2, acc[0][j][4 * g + 3] * r3);
;             *(u32x2*)(Vt + ((size_t)bh * 128 + j * 32 + r) * SEQ_ + sw + 8 * g + 4 * h) = o;
;         }
;     }
;     gemm_mainloop<128, 128, 32, 4, 1, 99>(tid, pa + (size_t)mt * 128 * LDPA + 512, LDPA, wt + (size_t)(hd * 256) * 256, 256, 256, smem, acc);
	v_pk_fma_f32 v[2:3], v[2:3], s[46:47], v[86:87] op_sel_hi:[1,0,0]
	s_nop 0
	v_mul_f32_e32 v6, 0x4b800000, v2
	v_cmp_gt_f32_e64 s[4:5], s53, v2
	v_cmp_gt_f32_e32 vcc, s53, v3
	v_pk_fma_f32 v[4:5], v[4:5], s[46:47], v[86:87] op_sel_hi:[1,0,0]
	v_cndmask_b32_e64 v2, v2, v6, s[4:5]
	v_mul_f32_e32 v6, 0x4b800000, v3
	v_cndmask_b32_e32 v3, v3, v6, vcc
	v_rsq_f32_e32 v2, v2
	v_rsq_f32_e32 v3, v3
	s_nop 0
	v_pk_mul_f32 v[6:7], v[2:3], s[50:51] op_sel_hi:[1,0]
	s_nop 0
	v_cndmask_b32_e32 v3, v3, v7, vcc
	v_cndmask_b32_e64 v2, v2, v6, s[4:5]
	v_pk_mul_f32 v[6:7], v[56:57], v[2:3]
	v_cmp_gt_f32_e64 s[4:5], s53, v4
	v_cvt_pk_bf16_f32 v6, v6, v7
	v_mul_f32_e32 v7, 0x4b800000, v4
	v_cmp_gt_f32_e32 vcc, s53, v5
	v_cndmask_b32_e64 v4, v4, v7, s[4:5]
	v_mul_f32_e32 v7, 0x4b800000, v5
	v_cndmask_b32_e32 v5, v5, v7, vcc
	v_rsq_f32_e32 v4, v4
	v_rsq_f32_e32 v5, v5
	s_nop 0
	v_pk_mul_f32 v[18:19], v[4:5], s[50:51] op_sel_hi:[1,0]
	s_nop 0
	v_cndmask_b32_e32 v5, v5, v19, vcc
	v_cndmask_b32_e64 v4, v4, v18, s[4:5]
	v_pk_mul_f32 v[18:19], v[58:59], v[4:5]
	s_nop 0
	v_cvt_pk_bf16_f32 v7, v18, v19
	global_store_dwordx2 v[50:51], v[6:7], off offset:32
	v_pk_mul_f32 v[6:7], v[40:41], v[2:3]
	v_pk_mul_f32 v[18:19], v[42:43], v[4:5]
	v_cvt_pk_bf16_f32 v6, v6, v7
	v_cvt_pk_bf16_f32 v7, v18, v19
	v_lshl_add_u64 v[18:19], v[0:1], 0, v[32:33]
	global_store_dwordx2 v[18:19], v[6:7], off
	v_pk_mul_f32 v[6:7], v[24:25], v[2:3]
	v_pk_mul_f32 v[18:19], v[26:27], v[4:5]
	v_pk_mul_f32 v[2:3], v[8:9], v[2:3]
	v_pk_mul_f32 v[4:5], v[10:11], v[4:5]
	v_cvt_pk_bf16_f32 v6, v6, v7
	v_cvt_pk_bf16_f32 v7, v18, v19
	v_lshl_add_u64 v[18:19], v[0:1], 0, v[16:17]
	v_cvt_pk_bf16_f32 v2, v2, v3
	v_cvt_pk_bf16_f32 v3, v4, v5
	v_lshl_add_u64 v[0:1], v[0:1], 0, v[48:49]
	global_store_dwordx2 v[18:19], v[6:7], off
	global_store_dwordx2 v[0:1], v[2:3], off
	global_load_dwordx4 v[0:3], v[82:83], off offset:96
	v_lshl_add_u64 v[4:5], v[84:85], 0, 48
	s_waitcnt vmcnt(0)
	v_pk_fma_f32 v[0:1], v[0:1], s[46:47], v[86:87] op_sel_hi:[1,0,0]
	s_nop 0
	v_mul_f32_e32 v6, 0x4b800000, v0
	v_cmp_gt_f32_e64 s[4:5], s53, v0
	v_cmp_gt_f32_e32 vcc, s53, v1
	v_pk_fma_f32 v[2:3], v[2:3], s[46:47], v[86:87] op_sel_hi:[1,0,0]
	v_cndmask_b32_e64 v0, v0, v6, s[4:5]
	v_mul_f32_e32 v6, 0x4b800000, v1
	v_cndmask_b32_e32 v1, v1, v6, vcc
	v_rsq_f32_e32 v0, v0
	v_rsq_f32_e32 v1, v1
	s_nop 0
	v_pk_mul_f32 v[6:7], v[0:1], s[50:51] op_sel_hi:[1,0]
	s_nop 0
	v_cndmask_b32_e32 v1, v1, v7, vcc
	v_cndmask_b32_e64 v0, v0, v6, s[4:5]
	v_pk_mul_f32 v[6:7], v[60:61], v[0:1]
	v_cmp_gt_f32_e64 s[4:5], s53, v2
	v_cvt_pk_bf16_f32 v6, v6, v7
	v_mul_f32_e32 v7, 0x4b800000, v2
	v_cmp_gt_f32_e32 vcc, s53, v3
	v_cndmask_b32_e64 v2, v2, v7, s[4:5]
	v_mul_f32_e32 v7, 0x4b800000, v3
	v_cndmask_b32_e32 v3, v3, v7, vcc
	v_rsq_f32_e32 v2, v2
	v_rsq_f32_e32 v3, v3
	s_nop 0
	v_pk_mul_f32 v[8:9], v[2:3], s[50:51] op_sel_hi:[1,0]
	s_nop 0
	v_cndmask_b32_e32 v3, v3, v9, vcc
	v_cndmask_b32_e64 v2, v2, v8, s[4:5]
	v_pk_mul_f32 v[8:9], v[62:63], v[2:3]
	s_nop 0
	v_cvt_pk_bf16_f32 v7, v8, v9
	global_store_dwordx2 v[50:51], v[6:7], off offset:48
	v_pk_mul_f32 v[6:7], v[44:45], v[0:1]
	v_pk_mul_f32 v[8:9], v[46:47], v[2:3]
	v_cvt_pk_bf16_f32 v6, v6, v7
	v_cvt_pk_bf16_f32 v7, v8, v9
	v_lshl_add_u64 v[8:9], v[4:5], 0, v[32:33]
	global_store_dwordx2 v[8:9], v[6:7], off
	v_pk_mul_f32 v[6:7], v[28:29], v[0:1]
	v_pk_mul_f32 v[8:9], v[30:31], v[2:3]
	v_pk_mul_f32 v[0:1], v[12:13], v[0:1]
	v_pk_mul_f32 v[2:3], v[14:15], v[2:3]
	v_cvt_pk_bf16_f32 v6, v6, v7
	v_cvt_pk_bf16_f32 v7, v8, v9
	v_lshl_add_u64 v[8:9], v[4:5], 0, v[16:17]
	v_cvt_pk_bf16_f32 v0, v0, v1
	v_cvt_pk_bf16_f32 v1, v2, v3
	v_lshl_add_u64 v[2:3], v[4:5], 0, v[48:49]
	global_store_dwordx2 v[8:9], v[6:7], off
	global_store_dwordx2 v[2:3], v[0:1], off
	global_load_dwordx4 v[0:3], v[66:67], off offset:1024
	s_nop 0
	global_load_dwordx4 v[4:7], v[68:69], off offset:1024
	v_lshl_add_u64 v[8:9], s[74:75], 0, v[76:77]
	v_lshl_add_u64 v[72:73], v[8:9], 0, v[72:73]
	v_lshl_add_u64 v[12:13], s[74:75], 0, v[74:75]
	global_load_dwordx4 v[8:11], v[72:73], off
	v_lshl_add_u64 v[70:71], v[12:13], 0, v[70:71]
	global_load_dwordx4 v[12:15], v[70:71], off
	s_waitcnt vmcnt(3)
	ds_write_b128 v93, v[0:3]
	s_waitcnt vmcnt(2)
	ds_write_b128 v94, v[4:7]
	s_waitcnt vmcnt(1)
	ds_write_b128 v93, v[8:11] offset:10240
	s_waitcnt vmcnt(0)
	ds_write_b128 v94, v[12:15] offset:10240
	s_waitcnt lgkmcnt(0)
	s_barrier
	global_load_dwordx4 v[74:77], v[66:67], off offset:1088
	global_load_dwordx4 v[82:85], v[68:69], off offset:1088
	global_load_dwordx4 v[86:89], v[72:73], off offset:64
	global_load_dwordx4 v[98:101], v[70:71], off offset:64
	ds_read_b128 v[0:3], v95 offset:12800
	ds_read_b128 v[4:7], v95 offset:15360
	ds_read_b128 v[8:11], v95 offset:17920
	ds_read_b128 v[12:15], v96
	ds_read_b128 v[102:105], v96 offset:32
	ds_read_b128 v[16:19], v95 offset:10240
	ds_read_b128 v[106:109], v95 offset:10272
	ds_read_b128 v[110:113], v95 offset:12832
	ds_read_b128 v[120:123], v95 offset:15392
	ds_read_b128 v[124:127], v95 offset:17952
	s_waitcnt vmcnt(3)
	ds_write_b128 v93, v[74:77] offset:20480
	s_waitcnt vmcnt(2)
	ds_write_b128 v94, v[82:85] offset:20480
	s_waitcnt vmcnt(1)
	ds_write_b128 v93, v[86:89] offset:30720
	s_waitcnt vmcnt(0)
	ds_write_b128 v94, v[98:101] offset:30720
	s_waitcnt lgkmcnt(0)
	s_barrier
; #define MFMA(a, b, c) __builtin_amdgcn_mfma_f32_32x32x16_bf16((a), (b), (c), 0, 0, 0)
; template <int BM, int BN, int BK, int WAVES_M, int WAVES_N, int UNSWAP_FROM>
; DI void gemm_mainloop(const int tid, const bf16_t* __restrict__ A, int lda, const bf16_t* __restrict__ Bt, int ldb, int K, unsigned char* smem,
;                       f32x16 (&acc)[BM / WAVES_M / 32][BN / WAVES_N / 32]) {
;     ...
;     for (int kt = 0; kt < nk; ++kt) {
;         const int buf = kt & 1;
;         if (kt + 1 < nk) G_LOAD(kt + 1);
;         const unsigned char* sa_ = smem + buf * STAGE; const unsigned char* sb_ = sa_ + A_ST;
; #pragma unroll
;         for (int ks = 0; ks < BK / 16; ++ks) {
;             bf16x8 af[WM], bfr[WN];
; #pragma unroll
;             for (int i = 0; i < WM; ++i) af[i] = *(const bf16x8*)(sa_ + (((wm * WM + i) * 32 + r) * LS + ks * 16 + h * 8) * 2);
; #pragma unroll
;             for (int j = 0; j < WN; ++j) bfr[j] = *(const bf16x8*)(sb_ + (((wn * WN + j) * 32 + r) * LS + ks * 16 + h * 8) * 2);
; #pragma unroll
;             for (int i = 0; i < WM; ++i)
; #pragma unroll
;                 for (int j = 0; j < WN; ++j) {
;                     if (j < UNSWAP_FROM) acc[i][j] = MFMA(bfr[j], af[i], acc[i][j]);
;                     else acc[i][j] = MFMA(af[i], bfr[j], acc[i][j]);
;                 }
;         }
;         if (kt + 1 < nk) G_STORE(buf ^ 1);
;         __syncthreads();
	global_load_dwordx4 v[74:77], v[66:67], off offset:1152
	global_load_dwordx4 v[82:85], v[68:69], off offset:1152
	global_load_dwordx4 v[86:89], v[72:73], off offset:128
	global_load_dwordx4 v[98:101], v[70:71], off offset:128
	v_mfma_f32_32x32x16_bf16 v[48:63], v[16:19], v[12:15], 0
	v_mfma_f32_32x32x16_bf16 v[32:47], v[0:3], v[12:15], 0
	v_mfma_f32_32x32x16_bf16 v[16:31], v[4:7], v[12:15], 0
	v_mfma_f32_32x32x16_bf16 v[0:15], v[8:11], v[12:15], 0
	v_mfma_f32_32x32x16_bf16 v[32:47], v[110:113], v[102:105], v[32:47]
	v_mfma_f32_32x32x16_bf16 v[16:31], v[120:123], v[102:105], v[16:31]
	v_mfma_f32_32x32x16_bf16 v[0:15], v[124:127], v[102:105], v[0:15]
	v_mfma_f32_32x32x16_bf16 v[48:63], v[106:109], v[102:105], v[48:63]
	ds_read_b128 v[102:105], v95 offset:33280
	ds_read_b128 v[106:109], v95 offset:35840
	ds_read_b128 v[110:113], v95 offset:38400
	ds_read_b128 v[120:123], v96 offset:20480
	ds_read_b128 v[124:127], v96 offset:20512
	ds_read_b128 v[128:131], v95 offset:30720
	ds_read_b128 v[132:135], v95 offset:30752
	s_waitcnt lgkmcnt(3)
	v_mfma_f32_32x32x16_bf16 v[32:47], v[102:105], v[120:123], v[32:47]
	v_mfma_f32_32x32x16_bf16 v[16:31], v[106:109], v[120:123], v[16:31]
	v_mfma_f32_32x32x16_bf16 v[0:15], v[110:113], v[120:123], v[0:15]
	ds_read_b128 v[102:105], v95 offset:33312
	ds_read_b128 v[106:109], v95 offset:35872
	ds_read_b128 v[110:113], v95 offset:38432
	s_waitcnt vmcnt(3)
	ds_write_b128 v93, v[74:77]
	s_waitcnt vmcnt(2)
	ds_write_b128 v94, v[82:85]
	s_waitcnt vmcnt(1)
	ds_write_b128 v93, v[86:89] offset:10240
	s_waitcnt vmcnt(0)
	ds_write_b128 v94, v[98:101] offset:10240
	s_waitcnt lgkmcnt(0)
	s_barrier
	global_load_dwordx4 v[74:77], v[66:67], off offset:1216
	global_load_dwordx4 v[82:85], v[68:69], off offset:1216
	global_load_dwordx4 v[86:89], v[72:73], off offset:192
	global_load_dwordx4 v[98:101], v[70:71], off offset:192
	v_mfma_f32_32x32x16_bf16 v[48:63], v[128:131], v[120:123], v[48:63]
	v_mfma_f32_32x32x16_bf16 v[32:47], v[102:105], v[124:127], v[32:47]
	v_mfma_f32_32x32x16_bf16 v[16:31], v[106:109], v[124:127], v[16:31]
	v_mfma_f32_32x32x16_bf16 v[0:15], v[110:113], v[124:127], v[0:15]
	v_mfma_f32_32x32x16_bf16 v[48:63], v[132:135], v[124:127], v[48:63]
	ds_read_b128 v[102:105], v95 offset:12800
	ds_read_b128 v[106:109], v95 offset:15360
	ds_read_b128 v[110:113], v95 offset:17920
	ds_read_b128 v[120:123], v96
	ds_read_b128 v[124:127], v96 offset:32
	ds_read_b128 v[128:131], v95 offset:10240
	ds_read_b128 v[132:135], v95 offset:10272
	s_waitcnt lgkmcnt(3)
	v_mfma_f32_32x32x16_bf16 v[32:47], v[102:105], v[120:123], v[32:47]
	v_mfma_f32_32x32x16_bf16 v[16:31], v[106:109], v[120:123], v[16:31]
	v_mfma_f32_32x32x16_bf16 v[0:15], v[110:113], v[120:123], v[0:15]
	ds_read_b128 v[102:105], v95 offset:12832
	ds_read_b128 v[106:109], v95 offset:15392
	ds_read_b128 v[110:113], v95 offset:17952
	s_waitcnt vmcnt(3)
	ds_write_b128 v93, v[74:77] offset:20480
	s_waitcnt vmcnt(2)
	ds_write_b128 v94, v[82:85] offset:20480
	s_waitcnt vmcnt(1)
	ds_write_b128 v93, v[86:89] offset:30720
	s_waitcnt vmcnt(0)
	ds_write_b128 v94, v[98:101] offset:30720
	s_waitcnt lgkmcnt(0)
	s_barrier
	global_load_dwordx4 v[74:77], v[66:67], off offset:1280
	global_load_dwordx4 v[82:85], v[68:69], off offset:1280
	global_load_dwordx4 v[86:89], v[72:73], off offset:256
	global_load_dwordx4 v[98:101], v[70:71], off offset:256
	v_mfma_f32_32x32x16_bf16 v[48:63], v[128:131], v[120:123], v[48:63]
	v_mfma_f32_32x32x16_bf16 v[32:47], v[102:105], v[124:127], v[32:47]
	v_mfma_f32_32x32x16_bf16 v[16:31], v[106:109], v[124:127], v[16:31]
	v_mfma_f32_32x32x16_bf16 v[0:15], v[110:113], v[124:127], v[0:15]
	v_mfma_f32_32x32x16_bf16 v[48:63], v[132:135], v[124:127], v[48:63]
	ds_read_b128 v[102:105], v95 offset:33280
	ds_read_b128 v[106:109], v95 offset:35840
	ds_read_b128 v[110:113], v95 offset:38400
	ds_read_b128 v[120:123], v96 offset:20480
	ds_read_b128 v[124:127], v96 offset:20512
	ds_read_b128 v[128:131], v95 offset:30720
	ds_read_b128 v[132:135], v95 offset:30752
	s_waitcnt lgkmcnt(3)
	v_mfma_f32_32x32x16_bf16 v[32:47], v[102:105], v[120:123], v[32:47]
	v_mfma_f32_32x32x16_bf16 v[16:31], v[106:109], v[120:123], v[16:31]
	v_mfma_f32_32x32x16_bf16 v[0:15], v[110:113], v[120:123], v[0:15]
	ds_read_b128 v[102:105], v95 offset:33312
	ds_read_b128 v[106:109], v95 offset:35872
	ds_read_b128 v[110:113], v95 offset:38432
	s_waitcnt vmcnt(3)
	ds_write_b128 v93, v[74:77]
	s_waitcnt vmcnt(2)
	ds_write_b128 v94, v[82:85]
	s_waitcnt vmcnt(1)
	ds_write_b128 v93, v[86:89] offset:10240
	s_waitcnt vmcnt(0)
	ds_write_b128 v94, v[98:101] offset:10240
	s_waitcnt lgkmcnt(0)
	s_barrier
	global_load_dwordx4 v[74:77], v[66:67], off offset:1344
	global_load_dwordx4 v[82:85], v[68:69], off offset:1344
	global_load_dwordx4 v[86:89], v[72:73], off offset:320
	global_load_dwordx4 v[98:101], v[70:71], off offset:320
	v_mfma_f32_32x32x16_bf16 v[48:63], v[128:131], v[120:123], v[48:63]
	v_mfma_f32_32x32x16_bf16 v[32:47], v[102:105], v[124:127], v[32:47]
	v_mfma_f32_32x32x16_bf16 v[16:31], v[106:109], v[124:127], v[16:31]
	v_mfma_f32_32x32x16_bf16 v[0:15], v[110:113], v[124:127], v[0:15]
	v_mfma_f32_32x32x16_bf16 v[48:63], v[132:135], v[124:127], v[48:63]
	ds_read_b128 v[102:105], v95 offset:12800
	ds_read_b128 v[106:109], v95 offset:15360
	ds_read_b128 v[110:113], v95 offset:17920
	ds_read_b128 v[120:123], v96
	ds_read_b128 v[124:127], v96 offset:32
	ds_read_b128 v[128:131], v95 offset:10240
	ds_read_b128 v[132:135], v95 offset:10272
	s_waitcnt lgkmcnt(3)
	v_mfma_f32_32x32x16_bf16 v[32:47], v[102:105], v[120:123], v[32:47]
	v_mfma_f32_32x32x16_bf16 v[16:31], v[106:109], v[120:123], v[16:31]
	v_mfma_f32_32x32x16_bf16 v[0:15], v[110:113], v[120:123], v[0:15]
	ds_read_b128 v[102:105], v95 offset:12832
	ds_read_b128 v[106:109], v95 offset:15392
	ds_read_b128 v[110:113], v95 offset:17952
	s_waitcnt vmcnt(3)
	ds_write_b128 v93, v[74:77] offset:20480
	s_waitcnt vmcnt(2)
	ds_write_b128 v94, v[82:85] offset:20480
	s_waitcnt vmcnt(1)
	ds_write_b128 v93, v[86:89] offset:30720
	s_waitcnt vmcnt(0)
	ds_write_b128 v94, v[98:101] offset:30720
	s_waitcnt lgkmcnt(0)
	s_barrier
; #define MFMA(a, b, c) __builtin_amdgcn_mfma_f32_32x32x16_bf16((a), (b), (c), 0, 0, 0)
; DI float bflo(unsigned u) { return __uint_as_float(u << 16); }
; template <int BM, int BN, int BK, int WAVES_M, int WAVES_N, int UNSWAP_FROM>
; DI void gemm_mainloop(const int tid, const bf16_t* __restrict__ A, int lda, const bf16_t* __restrict__ Bt, int ldb, int K, unsigned char* smem,
;                       f32x16 (&acc)[BM / WAVES_M / 32][BN / WAVES_N / 32]) {
;     ...
;     for (int kt = 0; kt < nk; ++kt) {
;         const int buf = kt & 1;
;         if (kt + 1 < nk) G_LOAD(kt + 1);
;         const unsigned char* sa_ = smem + buf * STAGE; const unsigned char* sb_ = sa_ + A_ST;
; #pragma unroll
;         for (int ks = 0; ks < BK / 16; ++ks) {
;             bf16x8 af[WM], bfr[WN];
; #pragma unroll
;             for (int i = 0; i < WM; ++i) af[i] = *(const bf16x8*)(sa_ + (((wm * WM + i) * 32 + r) * LS + ks * 16 + h * 8) * 2);
; #pragma unroll
;             for (int j = 0; j < WN; ++j) bfr[j] = *(const bf16x8*)(sb_ + (((wn * WN + j) * 32 + r) * LS + ks * 16 + h * 8) * 2);
; #pragma unroll
;             for (int i = 0; i < WM; ++i)
; #pragma unroll
;                 for (int j = 0; j < WN; ++j) {
;                     if (j < UNSWAP_FROM) acc[i][j] = MFMA(bfr[j], af[i], acc[i][j]);
;                     else acc[i][j] = MFMA(af[i], bfr[j], acc[i][j]);
;                 }
;         }
;         if (kt + 1 < nk) G_STORE(buf ^ 1);
;         __syncthreads();
; DI void kv_tile(const Params& p, int mt, int hd, unsigned char* smem) {
;     ...
;     const int m = mw + r, s = sw + r;
;     const float rkv = rsqrtf(ssq[m] * (1.f / 256.f) + EPS);
;     float ss = 0.f;
; #pragma unroll
;     for (int j = 0; j < 4; ++j)
; #pragma unroll
;         for (int e = 0; e < 16; ++e) { const float v = acc[0][j][e] * rkv; acc[0][j][e] = v; ss += v * v; }
;     float x1[16], x2[16];
; #pragma unroll
;     for (int g = 0; g < 4; ++g) {
;         const u32x2 a = *(const u32x2*)(pa + (size_t)m * LDPA + C_KR + 8 * g + 4 * h);
;         const u32x2 c = *(const u32x2*)(pa + (size_t)m * LDPA + C_KR + 32 + 8 * g + 4 * h);
;         x1[4 * g] = bflo(a.x); x1[4 * g + 1] = bfhi(a.x); x1[4 * g + 2] = bflo(a.y); x1[4 * g + 3] = bfhi(a.y);
;         x2[4 * g] = bflo(c.x); x2[4 * g + 1] = bfhi(c.x); x2[4 * g + 2] = bflo(c.y); x2[4 * g + 3] = bfhi(c.y);
;     }
	global_load_dwordx4 v[74:77], v[66:67], off offset:1408
	global_load_dwordx4 v[82:85], v[68:69], off offset:1408
	global_load_dwordx4 v[86:89], v[72:73], off offset:384
	global_load_dwordx4 v[98:101], v[70:71], off offset:384
	v_mfma_f32_32x32x16_bf16 v[48:63], v[128:131], v[120:123], v[48:63]
	v_mfma_f32_32x32x16_bf16 v[32:47], v[102:105], v[124:127], v[32:47]
	v_mfma_f32_32x32x16_bf16 v[16:31], v[106:109], v[124:127], v[16:31]
	v_mfma_f32_32x32x16_bf16 v[0:15], v[110:113], v[124:127], v[0:15]
	v_mfma_f32_32x32x16_bf16 v[48:63], v[132:135], v[124:127], v[48:63]
	ds_read_b128 v[102:105], v95 offset:33280
	ds_read_b128 v[106:109], v95 offset:35840
	ds_read_b128 v[110:113], v95 offset:38400
	ds_read_b128 v[120:123], v96 offset:20480
	ds_read_b128 v[124:127], v96 offset:20512
	ds_read_b128 v[128:131], v95 offset:30720
	ds_read_b128 v[132:135], v95 offset:30752
	s_waitcnt lgkmcnt(3)
	v_mfma_f32_32x32x16_bf16 v[32:47], v[102:105], v[120:123], v[32:47]
	v_mfma_f32_32x32x16_bf16 v[16:31], v[106:109], v[120:123], v[16:31]
	v_mfma_f32_32x32x16_bf16 v[0:15], v[110:113], v[120:123], v[0:15]
	ds_read_b128 v[102:105], v95 offset:33312
	ds_read_b128 v[106:109], v95 offset:35872
	ds_read_b128 v[110:113], v95 offset:38432
	s_waitcnt vmcnt(3)
	ds_write_b128 v93, v[74:77]
	s_waitcnt vmcnt(2)
	ds_write_b128 v94, v[82:85]
	s_waitcnt vmcnt(1)
	ds_write_b128 v93, v[86:89] offset:10240
	s_waitcnt vmcnt(0)
	ds_write_b128 v94, v[98:101] offset:10240
	s_waitcnt lgkmcnt(0)
	s_barrier
	global_load_dwordx4 v[74:77], v[66:67], off offset:1472
	s_nop 0
	global_load_dwordx4 v[66:69], v[68:69], off offset:1472
	s_nop 0
	global_load_dwordx4 v[82:85], v[72:73], off offset:448
	s_nop 0
	global_load_dwordx4 v[70:73], v[70:71], off offset:448
	v_mfma_f32_32x32x16_bf16 v[48:63], v[128:131], v[120:123], v[48:63]
	v_mfma_f32_32x32x16_bf16 v[32:47], v[102:105], v[124:127], v[32:47]
	v_mfma_f32_32x32x16_bf16 v[16:31], v[106:109], v[124:127], v[16:31]
	v_mfma_f32_32x32x16_bf16 v[0:15], v[110:113], v[124:127], v[0:15]
	v_mfma_f32_32x32x16_bf16 v[48:63], v[132:135], v[124:127], v[48:63]
	ds_read_b128 v[86:89], v95 offset:12800
	ds_read_b128 v[98:101], v95 offset:15360
	ds_read_b128 v[102:105], v95 offset:17920
	ds_read_b128 v[106:109], v96
	ds_read_b128 v[110:113], v96 offset:32
	ds_read_b128 v[120:123], v95 offset:10240
	ds_read_b128 v[124:127], v95 offset:10272
	s_waitcnt lgkmcnt(3)
	v_mfma_f32_32x32x16_bf16 v[32:47], v[86:89], v[106:109], v[32:47]
	v_mfma_f32_32x32x16_bf16 v[16:31], v[98:101], v[106:109], v[16:31]
	v_mfma_f32_32x32x16_bf16 v[0:15], v[102:105], v[106:109], v[0:15]
	ds_read_b128 v[86:89], v95 offset:12832
	ds_read_b128 v[98:101], v95 offset:15392
	ds_read_b128 v[102:105], v95 offset:17952
	s_waitcnt vmcnt(3)
	ds_write_b128 v93, v[74:77] offset:20480
	s_waitcnt vmcnt(2)
	ds_write_b128 v94, v[66:69] offset:20480
	s_waitcnt vmcnt(1)
	ds_write_b128 v93, v[82:85] offset:30720
	s_waitcnt vmcnt(0)
	ds_write_b128 v94, v[70:73] offset:30720
	s_waitcnt lgkmcnt(6)
	v_mfma_f32_32x32x16_bf16 v[32:47], v[86:89], v[110:113], v[32:47]
	s_waitcnt lgkmcnt(0)
	s_barrier
	v_mfma_f32_32x32x16_bf16 v[16:31], v[98:101], v[110:113], v[16:31]
	v_mfma_f32_32x32x16_bf16 v[0:15], v[102:105], v[110:113], v[0:15]
	ds_read_b128 v[66:69], v95 offset:33280
	ds_read_b128 v[70:73], v95 offset:35840
	ds_read_b128 v[74:77], v95 offset:38400
	ds_read_b128 v[82:85], v96 offset:20480
	ds_read_b128 v[86:89], v96 offset:20512
	ds_read_b128 v[98:101], v95 offset:30720
	ds_read_b128 v[102:105], v95 offset:30752
	v_mfma_f32_32x32x16_bf16 v[48:63], v[120:123], v[106:109], v[48:63]
	s_waitcnt lgkmcnt(3)
	v_mfma_f32_32x32x16_bf16 v[32:47], v[66:69], v[82:85], v[32:47]
	v_mfma_f32_32x32x16_bf16 v[16:31], v[70:73], v[82:85], v[16:31]
	v_mfma_f32_32x32x16_bf16 v[0:15], v[74:77], v[82:85], v[0:15]
	ds_read_b128 v[66:69], v95 offset:33312
	ds_read_b128 v[70:73], v95 offset:35872
	ds_read_b128 v[74:77], v95 offset:38432
	s_waitcnt lgkmcnt(0)
	s_barrier
	v_mfma_f32_32x32x16_bf16 v[48:63], v[124:127], v[110:113], v[48:63]
	v_lshlrev_b64 v[110:111], 2, v[64:65]
	v_mfma_f32_32x32x16_bf16 v[32:47], v[66:69], v[86:89], v[32:47]
	v_lshl_add_u64 v[66:67], s[76:77], 0, v[110:111]
	global_load_dword v65, v[66:67], off
	s_waitcnt vmcnt(0)
	v_fmamk_f32 v65, v65, 0x3b800000, v202
	v_cmp_gt_f32_e32 vcc, s53, v65
	v_mul_f32_e32 v66, 0x4b800000, v65
	v_mfma_f32_32x32x16_bf16 v[48:63], v[98:101], v[82:85], v[48:63]
	v_cndmask_b32_e32 v65, v65, v66, vcc
	v_rsq_f32_e32 v65, v65
	s_nop 0
	v_mul_f32_e32 v66, 0x45800000, v65
	v_cndmask_b32_e32 v176, v65, v66, vcc
	v_mov_b64_e32 v[66:67], s[8:9]
	v_mad_i64_i32 v[64:65], s[4:5], v64, s44, v[66:67]
	v_lshl_add_u64 v[64:65], v[64:65], 0, v[80:81]
	global_load_dwordx2 v[100:101], v[64:65], off offset:1536
	global_load_dwordx2 v[186:187], v[64:65], off offset:1600
	global_load_dwordx2 v[180:181], v[64:65], off offset:1552
	global_load_dwordx2 v[178:179], v[64:65], off offset:1616
	global_load_dwordx2 v[182:183], v[64:65], off offset:1568
	global_load_dwordx2 v[184:185], v[64:65], off offset:1632
	global_load_dwordx2 v[66:67], v[64:65], off offset:1584
	s_nop 0
	global_load_dwordx2 v[64:65], v[64:65], off offset:1648
	v_mfma_f32_32x32x16_bf16 v[48:63], v[102:105], v[86:89], v[48:63]
	v_readlane_b32 s4, v244, 31
	v_readlane_b32 s5, v244, 32
	s_movk_i32 s44, 0x180
	v_mul_f32_e64 v90, v32, v176
	v_mul_f32_e64 v91, v33, v176
	s_waitcnt vmcnt(3)
	v_and_b32_e32 v82, 0xffff0000, v183
	s_nop 4
	v_pk_mul_f32 v[108:109], v[48:49], v[176:177] op_sel_hi:[1,0]
	v_pk_mul_f32 v[106:107], v[50:51], v[176:177] op_sel_hi:[1,0]
	v_pk_mul_f32 v[146:147], v[108:109], v[108:109]
	v_pk_mul_f32 v[112:113], v[106:107], v[106:107]
	v_add_f32_e32 v119, v146, v147
	v_mfma_f32_32x32x16_bf16 v[0:15], v[74:77], v[86:89], v[0:15]
	s_waitcnt vmcnt(2)
; DI float bflo(unsigned u) { return __uint_as_float(u << 16); }
; DI float bfhi(unsigned u) { return __uint_as_float(u & 0xffff0000u); }
; DI void kv_tile(const Params& p, int mt, int hd, unsigned char* smem) {
;     ...
;     const int m = mw + r, s = sw + r;
;     const float rkv = rsqrtf(ssq[m] * (1.f / 256.f) + EPS);
;     float ss = 0.f;
; #pragma unroll
;     for (int j = 0; j < 4; ++j)
; #pragma unroll
;         for (int e = 0; e < 16; ++e) { const float v = acc[0][j][e] * rkv; acc[0][j][e] = v; ss += v * v; }
;     float x1[16], x2[16];
; #pragma unroll
;     for (int g = 0; g < 4; ++g) {
;         const u32x2 a = *(const u32x2*)(pa + (size_t)m * LDPA + C_KR + 8 * g + 4 * h);
;         const u32x2 c = *(const u32x2*)(pa + (size_t)m * LDPA + C_KR + 32 + 8 * g + 4 * h);
;         x1[4 * g] = bflo(a.x); x1[4 * g + 1] = bfhi(a.x); x1[4 * g + 2] = bflo(a.y); x1[4 * g + 3] = bfhi(a.y);
;         x2[4 * g] = bflo(c.x); x2[4 * g + 1] = bfhi(c.x); x2[4 * g + 2] = bflo(c.y); x2[4 * g + 3] = bfhi(c.y);
;     }
; #pragma unroll
;     for (int e = 0; e < 16; ++e) ss += x1[e] * x1[e] + x2[e] * x2[e];
;     ss += __shfl_xor(ss, 32);
;     const float rs = rsqrtf(ss * (1.f / 192.f) + EPS);
	v_and_b32_e32 v76, 0xffff0000, v185
	v_lshlrev_b32_e32 v77, 16, v185
	v_mul_f32_e64 v104, v52, v176
	v_mul_f32_e64 v105, v53, v176
	v_add_f32_e32 v112, v112, v119
	v_lshlrev_b32_e32 v83, 16, v183
	v_pk_mul_f32 v[68:69], v[76:77], v[76:77]
	v_pk_mul_f32 v[148:149], v[104:105], v[104:105]
	v_mfma_f32_32x32x16_bf16 v[16:31], v[70:73], v[86:89], v[16:31]
	s_waitcnt vmcnt(0)
	v_and_b32_e32 v72, 0xffff0000, v64
	v_lshlrev_b32_e32 v73, 16, v64
	v_add_f32_e32 v112, v113, v112
	v_fma_f32 v84, v82, v82, v68
	v_fma_f32 v85, v83, v83, v69
	v_and_b32_e32 v74, 0xffff0000, v66
	v_lshlrev_b32_e32 v75, 16, v66
	v_pk_mul_f32 v[68:69], v[72:73], v[72:73]
	v_pk_mul_f32 v[102:103], v[54:55], v[176:177] op_sel_hi:[1,0]
	v_add_f32_e32 v112, v148, v112
	v_pk_fma_f32 v[86:87], v[74:75], v[74:75], v[68:69]
	v_and_b32_e32 v68, 0xffff0000, v65
	v_lshlrev_b32_e32 v69, 16, v65
	v_pk_mul_f32 v[114:115], v[102:103], v[102:103]
	v_add_f32_e32 v112, v149, v112
	v_and_b32_e32 v70, 0xffff0000, v67
	v_lshlrev_b32_e32 v71, 16, v67
	v_pk_mul_f32 v[64:65], v[68:69], v[68:69]
	v_pk_mul_f32 v[98:99], v[56:57], v[176:177] op_sel_hi:[1,0]
	v_add_f32_e32 v112, v114, v112
	v_pk_fma_f32 v[88:89], v[70:71], v[70:71], v[64:65]
	v_lshlrev_b64 v[64:65], 13, v[78:79]
	v_pk_mul_f32 v[150:151], v[98:99], v[98:99]
	v_add_f32_e32 v112, v115, v112
	v_or3_b32 v64, v97, v92, v64
	v_pk_mul_f32 v[96:97], v[58:59], v[176:177] op_sel_hi:[1,0]
	v_add_f32_e32 v112, v150, v112
	v_pk_mul_f32 v[120:121], v[96:97], v[96:97]
	v_add_f32_e32 v112, v151, v112
	v_pk_mul_f32 v[94:95], v[60:61], v[176:177] op_sel_hi:[1,0]
	v_add_f32_e32 v112, v120, v112
	v_pk_mul_f32 v[152:153], v[94:95], v[94:95]
	v_add_f32_e32 v112, v121, v112
	v_pk_mul_f32 v[92:93], v[62:63], v[176:177] op_sel_hi:[1,0]
	v_add_f32_e32 v112, v152, v112
	v_mov_b64_e32 v[66:67], s[4:5]
	v_pk_mul_f32 v[122:123], v[92:93], v[92:93]
	v_add_f32_e32 v112, v153, v112
	v_mad_u64_u32 v[78:79], s[4:5], v64, s44, v[66:67]
	v_add_f32_e32 v112, v122, v112
	v_mad_i32_i24 v79, v65, s44, v79
	v_pk_mul_f32 v[154:155], v[90:91], v[90:91]
	v_add_f32_e32 v112, v123, v112
	global_load_dwordx4 v[64:67], v116, s[58:59]
	v_lshl_add_u64 v[48:49], v[78:79], 0, v[80:81]
	v_pk_mul_f32 v[80:81], v[34:35], v[176:177] op_sel_hi:[1,0]
	v_add_f32_e32 v112, v154, v112
	v_pk_mul_f32 v[124:125], v[80:81], v[80:81]
	v_add_f32_e32 v112, v155, v112
	v_pk_mul_f32 v[78:79], v[36:37], v[176:177] op_sel_hi:[1,0]
	v_add_f32_e32 v112, v124, v112
	v_pk_mul_f32 v[156:157], v[78:79], v[78:79]
	v_add_f32_e32 v112, v125, v112
	v_pk_mul_f32 v[62:63], v[38:39], v[176:177] op_sel_hi:[1,0]
	v_add_f32_e32 v112, v156, v112
	v_pk_mul_f32 v[126:127], v[62:63], v[62:63]
	v_add_f32_e32 v112, v157, v112
	v_pk_mul_f32 v[60:61], v[40:41], v[176:177] op_sel_hi:[1,0]
	v_add_f32_e32 v112, v126, v112
	v_pk_mul_f32 v[158:159], v[60:61], v[60:61]
	v_add_f32_e32 v112, v127, v112
	v_pk_mul_f32 v[58:59], v[42:43], v[176:177] op_sel_hi:[1,0]
	v_add_f32_e32 v112, v158, v112
	v_pk_mul_f32 v[128:129], v[58:59], v[58:59]
	v_add_f32_e32 v112, v159, v112
	v_pk_mul_f32 v[56:57], v[44:45], v[176:177] op_sel_hi:[1,0]
	v_add_f32_e32 v112, v128, v112
	v_pk_mul_f32 v[160:161], v[56:57], v[56:57]
	v_add_f32_e32 v112, v129, v112
	v_pk_mul_f32 v[54:55], v[46:47], v[176:177] op_sel_hi:[1,0]
	v_add_f32_e32 v112, v160, v112
	v_pk_mul_f32 v[130:131], v[54:55], v[54:55]
	v_add_f32_e32 v112, v161, v112
	v_pk_mul_f32 v[52:53], v[16:17], v[176:177] op_sel_hi:[1,0]
	v_add_f32_e32 v112, v130, v112
	v_pk_mul_f32 v[162:163], v[52:53], v[52:53]
	v_add_f32_e32 v112, v131, v112
	v_pk_mul_f32 v[46:47], v[18:19], v[176:177] op_sel_hi:[1,0]
	v_add_f32_e32 v112, v162, v112
	v_pk_mul_f32 v[132:133], v[46:47], v[46:47]
	v_add_f32_e32 v112, v163, v112
	v_pk_mul_f32 v[42:43], v[20:21], v[176:177] op_sel_hi:[1,0]
	v_add_f32_e32 v112, v132, v112
	v_pk_mul_f32 v[164:165], v[42:43], v[42:43]
	v_add_f32_e32 v112, v133, v112
	v_pk_mul_f32 v[40:41], v[22:23], v[176:177] op_sel_hi:[1,0]
	v_add_f32_e32 v112, v164, v112
	v_pk_mul_f32 v[134:135], v[40:41], v[40:41]
	v_add_f32_e32 v112, v165, v112
	v_pk_mul_f32 v[38:39], v[24:25], v[176:177] op_sel_hi:[1,0]
	v_add_f32_e32 v112, v134, v112
	v_pk_mul_f32 v[166:167], v[38:39], v[38:39]
	v_add_f32_e32 v112, v135, v112
	v_pk_mul_f32 v[36:37], v[26:27], v[176:177] op_sel_hi:[1,0]
	v_add_f32_e32 v112, v166, v112
	v_pk_mul_f32 v[136:137], v[36:37], v[36:37]
	v_add_f32_e32 v112, v167, v112
	v_pk_mul_f32 v[34:35], v[28:29], v[176:177] op_sel_hi:[1,0]
	v_add_f32_e32 v112, v136, v112
	v_pk_mul_f32 v[168:169], v[34:35], v[34:35]
	v_add_f32_e32 v112, v137, v112
	v_pk_mul_f32 v[32:33], v[30:31], v[176:177] op_sel_hi:[1,0]
	v_add_f32_e32 v112, v168, v112
	v_pk_mul_f32 v[138:139], v[32:33], v[32:33]
	v_add_f32_e32 v112, v169, v112
	v_pk_mul_f32 v[30:31], v[0:1], v[176:177] op_sel_hi:[1,0]
	v_add_f32_e32 v112, v138, v112
	v_pk_mul_f32 v[170:171], v[30:31], v[30:31]
	v_add_f32_e32 v112, v139, v112
	v_pk_mul_f32 v[28:29], v[2:3], v[176:177] op_sel_hi:[1,0]
	v_add_f32_e32 v112, v170, v112
	v_pk_mul_f32 v[140:141], v[28:29], v[28:29]
	v_add_f32_e32 v112, v171, v112
	v_pk_mul_f32 v[26:27], v[4:5], v[176:177] op_sel_hi:[1,0]
	v_add_f32_e32 v112, v140, v112
	v_pk_mul_f32 v[172:173], v[26:27], v[26:27]
	v_add_f32_e32 v112, v141, v112
	v_pk_mul_f32 v[24:25], v[6:7], v[176:177] op_sel_hi:[1,0]
	v_add_f32_e32 v112, v172, v112
	v_pk_mul_f32 v[0:1], v[24:25], v[24:25]
	v_add_f32_e32 v112, v173, v112
	v_pk_mul_f32 v[20:21], v[8:9], v[176:177] op_sel_hi:[1,0]
	v_add_f32_e32 v0, v0, v112
	v_pk_mul_f32 v[174:175], v[20:21], v[20:21]
	v_add_f32_e32 v0, v1, v0
	v_pk_mul_f32 v[18:19], v[10:11], v[176:177] op_sel_hi:[1,0]
	v_add_f32_e32 v0, v174, v0
; DI unsigned pk2(float a, float b) { f2_t v = {a, b}; bf2_t r = __builtin_convertvector(v, bf2_t); return __builtin_bit_cast(unsigned, r); }
; DI void kv_tile(const Params& p, int mt, int hd, unsigned char* smem) {
;     ...
;     for (int e = 0; e < 16; ++e) ss += x1[e] * x1[e] + x2[e] * x2[e];
;     ss += __shfl_xor(ss, 32);
;     const float rs = rsqrtf(ss * (1.f / 192.f) + EPS);
;     bf16_t* krow = Kb + ((size_t)bh * SEQ_ + s) * 192;
; #pragma unroll
;     for (int j = 0; j < 4; ++j)
; #pragma unroll
;         for (int g = 0; g < 4; ++g) {
;             const int n = j * 32 + 8 * g + 4 * h;
;             const f32x4 gn = *(const f32x4*)(p.k_gain + n);
;             u32x2 o; o.x = pk2(acc[0][j][4 * g] * rs * gn.x, acc[0][j][4 * g + 1] * rs * gn.y);
;             o.y = pk2(acc[0][j][4 * g + 2] * rs * gn.z, acc[0][j][4 * g + 3] * rs * gn.w);
;             *(u32x2*)(krow + n) = o;
;         }
	v_pk_mul_f32 v[142:143], v[18:19], v[18:19]
	v_add_f32_e32 v0, v175, v0
	v_pk_mul_f32 v[16:17], v[12:13], v[176:177] op_sel_hi:[1,0]
	v_add_f32_e32 v0, v142, v0
	v_pk_mul_f32 v[14:15], v[14:15], v[176:177] op_sel_hi:[1,0]
	v_pk_mul_f32 v[176:177], v[16:17], v[16:17]
	v_add_f32_e32 v0, v143, v0
	v_lshlrev_b32_e32 v44, 16, v187
	v_and_b32_e32 v45, 0xffff0000, v187
	v_add_f32_e32 v0, v176, v0
	v_pk_mul_f32 v[144:145], v[14:15], v[14:15]
	v_lshl_add_u64 v[10:11], s[42:43], 0, v[110:111]
	v_lshlrev_b32_e32 v50, 16, v101
	v_and_b32_e32 v51, 0xffff0000, v101
	v_pk_mul_f32 v[2:3], v[44:45], v[44:45]
	v_lshlrev_b32_e32 v110, 16, v100
	v_and_b32_e32 v111, 0xffff0000, v100
	v_lshlrev_b32_e32 v100, 16, v186
	v_and_b32_e32 v101, 0xffff0000, v186
	v_add_f32_e32 v0, v177, v0
	v_pk_fma_f32 v[188:189], v[50:51], v[50:51], v[2:3]
	v_pk_mul_f32 v[2:3], v[100:101], v[100:101]
	v_add_f32_e32 v0, v144, v0
	v_pk_fma_f32 v[186:187], v[110:111], v[110:111], v[2:3]
	v_add_f32_e32 v0, v145, v0
	v_lshlrev_b32_e32 v6, 16, v179
	v_and_b32_e32 v7, 0xffff0000, v179
	v_add_f32_e32 v0, v186, v0
	v_lshlrev_b32_e32 v8, 16, v181
	v_and_b32_e32 v9, 0xffff0000, v181
	v_pk_mul_f32 v[2:3], v[6:7], v[6:7]
	v_lshlrev_b32_e32 v12, 16, v178
	v_and_b32_e32 v13, 0xffff0000, v178
	v_add_f32_e32 v0, v187, v0
	v_pk_fma_f32 v[190:191], v[8:9], v[8:9], v[2:3]
	v_lshlrev_b32_e32 v22, 16, v180
	v_and_b32_e32 v23, 0xffff0000, v180
	v_pk_mul_f32 v[2:3], v[12:13], v[12:13]
	v_add_f32_e32 v0, v188, v0
	v_pk_fma_f32 v[178:179], v[22:23], v[22:23], v[2:3]
	v_add_f32_e32 v0, v189, v0
	v_add_f32_e32 v0, v178, v0
	v_lshlrev_b32_e32 v2, 16, v184
	v_and_b32_e32 v3, 0xffff0000, v184
	v_add_f32_e32 v0, v179, v0
	v_lshlrev_b32_e32 v4, 16, v182
	v_and_b32_e32 v5, 0xffff0000, v182
	v_pk_mul_f32 v[180:181], v[2:3], v[2:3]
	v_add_f32_e32 v0, v190, v0
	v_pk_fma_f32 v[180:181], v[4:5], v[4:5], v[180:181]
	v_add_f32_e32 v0, v191, v0
	v_add_f32_e32 v0, v180, v0
	v_add_f32_e32 v0, v181, v0
	v_add_f32_e32 v0, v85, v0
	v_add_f32_e32 v0, v84, v0
	v_add_f32_e32 v0, v87, v0
	v_add_f32_e32 v0, v86, v0
	v_add_f32_e32 v0, v89, v0
	v_add_f32_e32 v0, v88, v0
	ds_bpermute_b32 v1, v241, v0
	s_mov_b64 s[4:5], 0
	s_waitcnt lgkmcnt(0)
	v_add_f32_e32 v0, v0, v1
	v_fmamk_f32 v0, v0, 0x3baaaaab, v202
	v_cmp_gt_f32_e32 vcc, s53, v0
	v_mul_f32_e32 v1, 0x4b800000, v0
	s_nop 0
	v_cndmask_b32_e32 v0, v0, v1, vcc
	v_rsq_f32_e32 v0, v0
	s_nop 0
	v_mul_f32_e32 v1, 0x45800000, v0
	v_cndmask_b32_e32 v0, v0, v1, vcc
	v_pk_mul_f32 v[84:85], v[108:109], v[0:1] op_sel_hi:[1,0]
	v_pk_mul_f32 v[80:81], v[80:81], v[0:1] op_sel_hi:[1,0]
	s_waitcnt vmcnt(0)
	v_pk_mul_f32 v[64:65], v[64:65], v[84:85]
	v_pk_mul_f32 v[84:85], v[106:107], v[0:1] op_sel_hi:[1,0]
	v_cvt_pk_bf16_f32 v64, v64, v65
	v_pk_mul_f32 v[66:67], v[66:67], v[84:85]
	v_pk_mul_f32 v[84:85], v[104:105], v[0:1] op_sel_hi:[1,0]
	v_cvt_pk_bf16_f32 v65, v66, v67
	global_store_dwordx2 v[48:49], v[64:65], off
	global_load_dwordx4 v[228:231], v116, s[58:59] offset:32
	global_load_dwordx4 v[232:235], v116, s[58:59] offset:64
	global_load_dwordx4 v[222:225], v116, s[58:59] offset:96
	v_pk_mul_f32 v[78:79], v[78:79], v[0:1] op_sel_hi:[1,0]
	v_pk_mul_f32 v[62:63], v[62:63], v[0:1] op_sel_hi:[1,0]
	v_pk_mul_f32 v[60:61], v[60:61], v[0:1] op_sel_hi:[1,0]
	v_pk_mul_f32 v[58:59], v[58:59], v[0:1] op_sel_hi:[1,0]
	v_pk_mul_f32 v[56:57], v[56:57], v[0:1] op_sel_hi:[1,0]
	v_pk_mul_f32 v[54:55], v[54:55], v[0:1] op_sel_hi:[1,0]
	v_pk_mul_f32 v[52:53], v[52:53], v[0:1] op_sel_hi:[1,0]
	v_pk_mul_f32 v[46:47], v[46:47], v[0:1] op_sel_hi:[1,0]
	v_pk_mul_f32 v[42:43], v[42:43], v[0:1] op_sel_hi:[1,0]
	v_pk_mul_f32 v[40:41], v[40:41], v[0:1] op_sel_hi:[1,0]
	v_pk_mul_f32 v[38:39], v[38:39], v[0:1] op_sel_hi:[1,0]
	v_pk_mul_f32 v[36:37], v[36:37], v[0:1] op_sel_hi:[1,0]
	v_pk_mul_f32 v[34:35], v[34:35], v[0:1] op_sel_hi:[1,0]
	v_pk_mul_f32 v[32:33], v[32:33], v[0:1] op_sel_hi:[1,0]
	v_pk_mul_f32 v[30:31], v[30:31], v[0:1] op_sel_hi:[1,0]
	v_pk_mul_f32 v[28:29], v[28:29], v[0:1] op_sel_hi:[1,0]
	v_pk_mul_f32 v[26:27], v[26:27], v[0:1] op_sel_hi:[1,0]
	v_pk_mul_f32 v[24:25], v[24:25], v[0:1] op_sel_hi:[1,0]
	v_pk_mul_f32 v[20:21], v[20:21], v[0:1] op_sel_hi:[1,0]
	v_pk_mul_f32 v[18:19], v[18:19], v[0:1] op_sel_hi:[1,0]
	v_pk_mul_f32 v[16:17], v[16:17], v[0:1] op_sel_hi:[1,0]
	v_pk_mul_f32 v[14:15], v[14:15], v[0:1] op_sel_hi:[1,0]
	s_waitcnt vmcnt(2)
	v_pk_mul_f32 v[64:65], v[228:229], v[84:85]
	v_pk_mul_f32 v[84:85], v[102:103], v[0:1] op_sel_hi:[1,0]
	v_cvt_pk_bf16_f32 v64, v64, v65
	v_pk_mul_f32 v[66:67], v[230:231], v[84:85]
	v_pk_mul_f32 v[84:85], v[98:99], v[0:1] op_sel_hi:[1,0]
	v_cvt_pk_bf16_f32 v65, v66, v67
	global_store_dwordx2 v[48:49], v[64:65], off offset:16
	global_load_dwordx4 v[228:231], v116, s[58:59] offset:128
	s_waitcnt vmcnt(3)
	v_pk_mul_f32 v[64:65], v[232:233], v[84:85]
	v_pk_mul_f32 v[84:85], v[96:97], v[0:1] op_sel_hi:[1,0]
	v_cvt_pk_bf16_f32 v64, v64, v65
	v_pk_mul_f32 v[66:67], v[234:235], v[84:85]
	v_pk_mul_f32 v[84:85], v[94:95], v[0:1] op_sel_hi:[1,0]
	v_cvt_pk_bf16_f32 v65, v66, v67
	global_store_dwordx2 v[48:49], v[64:65], off offset:32
	global_load_dwordx4 v[232:235], v116, s[58:59] offset:160
	s_waitcnt vmcnt(4)
	v_pk_mul_f32 v[64:65], v[222:223], v[84:85]
	v_pk_mul_f32 v[84:85], v[92:93], v[0:1] op_sel_hi:[1,0]
	v_cvt_pk_bf16_f32 v64, v64, v65
	v_pk_mul_f32 v[66:67], v[224:225], v[84:85]
	v_pk_mul_f32 v[84:85], v[90:91], v[0:1] op_sel_hi:[1,0]
	v_cvt_pk_bf16_f32 v65, v66, v67
	global_store_dwordx2 v[48:49], v[64:65], off offset:48
	global_load_dwordx4 v[222:225], v116, s[58:59] offset:192
	s_waitcnt vmcnt(4)
; DI unsigned pk2(float a, float b) { f2_t v = {a, b}; bf2_t r = __builtin_convertvector(v, bf2_t); return __builtin_bit_cast(unsigned, r); }
; DI void kv_tile(const Params& p, int mt, int hd, unsigned char* smem) {
;     ...
; #pragma unroll
;     for (int j = 0; j < 4; ++j)
; #pragma unroll
;         for (int g = 0; g < 4; ++g) {
;             const int n = j * 32 + 8 * g + 4 * h;
;             const f32x4 gn = *(const f32x4*)(p.k_gain + n);
;             u32x2 o; o.x = pk2(acc[0][j][4 * g] * rs * gn.x, acc[0][j][4 * g + 1] * rs * gn.y);
;             o.y = pk2(acc[0][j][4 * g + 2] * rs * gn.z, acc[0][j][4 * g + 3] * rs * gn.w);
;             *(u32x2*)(krow + n) = o;
;         }
;     const float posf = (float)p.pos[m];
;     const float* invf = (const float*)(p.ws + WS_CTRL + 256);
; #pragma unroll
;     for (int g = 0; g < 4; ++g) {
;         float o1[4], o2[4];
; #pragma unroll
;         for (int jj = 0; jj < 4; ++jj) {
;             const int i = 8 * g + 4 * h + jj;
;             float sn, cs; sincos_rev(posf * invf[i], sn, cs);
;             const float y1 = x1[4 * g + jj] * rs * p.k_gain[128 + i], y2 = x2[4 * g + jj] * rs * p.k_gain[160 + i];
;             o1[jj] = y1 * cs - y2 * sn; o2[jj] = y2 * cs + y1 * sn;
;         }
;         u32x2 a; a.x = pk2(o1[0], o1[1]); a.y = pk2(o1[2], o1[3]);
;         u32x2 c; c.x = pk2(o2[0], o2[1]); c.y = pk2(o2[2], o2[3]);
;         *(u32x2*)(krow + 128 + 8 * g + 4 * h) = a;
;         *(u32x2*)(krow + 160 + 8 * g + 4 * h) = c;
;     }
	v_pk_mul_f32 v[64:65], v[228:229], v[84:85]
	v_pk_mul_f32 v[66:67], v[230:231], v[80:81]
	v_cvt_pk_bf16_f32 v64, v64, v65
	v_cvt_pk_bf16_f32 v65, v66, v67
	global_store_dwordx2 v[48:49], v[64:65], off offset:64
	global_load_dwordx4 v[228:231], v116, s[58:59] offset:224
	s_waitcnt vmcnt(4)
	v_pk_mul_f32 v[64:65], v[232:233], v[78:79]
	v_pk_mul_f32 v[62:63], v[234:235], v[62:63]
	v_cvt_pk_bf16_f32 v64, v64, v65
	v_cvt_pk_bf16_f32 v65, v62, v63
	global_store_dwordx2 v[48:49], v[64:65], off offset:80
	global_load_dwordx4 v[232:235], v116, s[58:59] offset:256
	s_waitcnt vmcnt(4)
	v_pk_mul_f32 v[60:61], v[222:223], v[60:61]
	v_pk_mul_f32 v[58:59], v[224:225], v[58:59]
	v_cvt_pk_bf16_f32 v60, v60, v61
	v_cvt_pk_bf16_f32 v61, v58, v59
	global_store_dwordx2 v[48:49], v[60:61], off offset:96
	global_load_dwordx4 v[222:225], v116, s[58:59] offset:288
	s_waitcnt vmcnt(4)
	v_pk_mul_f32 v[56:57], v[228:229], v[56:57]
	v_pk_mul_f32 v[54:55], v[230:231], v[54:55]
	v_cvt_pk_bf16_f32 v56, v56, v57
	v_cvt_pk_bf16_f32 v57, v54, v55
	global_store_dwordx2 v[48:49], v[56:57], off offset:112
	global_load_dwordx4 v[228:231], v116, s[58:59] offset:320
	s_waitcnt vmcnt(4)
	v_pk_mul_f32 v[52:53], v[232:233], v[52:53]
	v_pk_mul_f32 v[46:47], v[234:235], v[46:47]
	v_cvt_pk_bf16_f32 v52, v52, v53
	v_cvt_pk_bf16_f32 v53, v46, v47
	global_store_dwordx2 v[48:49], v[52:53], off offset:128
	global_load_dwordx4 v[232:235], v116, s[58:59] offset:352
	s_waitcnt vmcnt(4)
	v_pk_mul_f32 v[42:43], v[222:223], v[42:43]
	v_pk_mul_f32 v[40:41], v[224:225], v[40:41]
	v_cvt_pk_bf16_f32 v42, v42, v43
	v_cvt_pk_bf16_f32 v43, v40, v41
	global_store_dwordx2 v[48:49], v[42:43], off offset:144
	global_load_dwordx4 v[222:225], v116, s[58:59] offset:384
	s_waitcnt vmcnt(4)
	v_pk_mul_f32 v[38:39], v[228:229], v[38:39]
	v_pk_mul_f32 v[36:37], v[230:231], v[36:37]
	v_cvt_pk_bf16_f32 v38, v38, v39
	v_cvt_pk_bf16_f32 v39, v36, v37
	global_store_dwordx2 v[48:49], v[38:39], off offset:160
	global_load_dwordx4 v[228:231], v116, s[58:59] offset:416
	s_waitcnt vmcnt(4)
	v_pk_mul_f32 v[34:35], v[232:233], v[34:35]
	v_pk_mul_f32 v[32:33], v[234:235], v[32:33]
	v_cvt_pk_bf16_f32 v34, v34, v35
	v_cvt_pk_bf16_f32 v35, v32, v33
	global_store_dwordx2 v[48:49], v[34:35], off offset:176
	global_load_dwordx4 v[232:235], v116, s[58:59] offset:448
	s_waitcnt vmcnt(4)
	v_pk_mul_f32 v[30:31], v[222:223], v[30:31]
	v_pk_mul_f32 v[28:29], v[224:225], v[28:29]
	v_cvt_pk_bf16_f32 v30, v30, v31
	v_cvt_pk_bf16_f32 v31, v28, v29
	global_store_dwordx2 v[48:49], v[30:31], off offset:192
	global_load_dwordx4 v[222:225], v116, s[58:59] offset:480
	s_waitcnt vmcnt(4)
	v_pk_mul_f32 v[26:27], v[228:229], v[26:27]
	v_pk_mul_f32 v[24:25], v[230:231], v[24:25]
	v_cvt_pk_bf16_f32 v26, v26, v27
	v_cvt_pk_bf16_f32 v27, v24, v25
	global_store_dwordx2 v[48:49], v[26:27], off offset:208
	s_waitcnt vmcnt(3)
	v_pk_mul_f32 v[20:21], v[232:233], v[20:21]
	v_pk_mul_f32 v[18:19], v[234:235], v[18:19]
	v_cvt_pk_bf16_f32 v20, v20, v21
	v_cvt_pk_bf16_f32 v21, v18, v19
	global_store_dwordx2 v[48:49], v[20:21], off offset:224
	s_waitcnt vmcnt(2)
	v_pk_mul_f32 v[16:17], v[222:223], v[16:17]
	v_pk_mul_f32 v[14:15], v[224:225], v[14:15]
	v_cvt_pk_bf16_f32 v16, v16, v17
	v_cvt_pk_bf16_f32 v17, v14, v15
	global_store_dwordx2 v[48:49], v[16:17], off offset:240
	global_load_dword v1, v[10:11], off
	global_load_dwordx4 v[18:21], v116, s[58:59] offset:512
	s_waitcnt vmcnt(1)
	v_cvt_f32_i32_e32 v1, v1
	global_load_dwordx4 v[14:17], v116, s[72:73] offset:256
	v_pk_mul_f32 v[24:25], v[0:1], v[110:111] op_sel_hi:[0,1]
	s_waitcnt vmcnt(1)
	v_pk_mul_f32 v[18:19], v[18:19], v[24:25]
	global_load_dwordx4 v[24:27], v116, s[58:59] offset:640
	v_pk_mul_f32 v[30:31], v[0:1], v[100:101] op_sel_hi:[0,1]
	v_pk_mul_f32 v[22:23], v[0:1], v[22:23] op_sel_hi:[0,1]
	v_pk_mul_f32 v[12:13], v[0:1], v[12:13] op_sel_hi:[0,1]
	v_pk_mul_f32 v[6:7], v[0:1], v[6:7] op_sel_hi:[0,1]
	v_pk_mul_f32 v[8:9], v[0:1], v[8:9] op_sel_hi:[0,1]
	v_pk_mul_f32 v[4:5], v[0:1], v[4:5] op_sel_hi:[0,1]
	v_pk_mul_f32 v[2:3], v[0:1], v[2:3] op_sel_hi:[0,1]
	s_waitcnt vmcnt(1)
	v_mul_f32_e32 v10, v14, v1
	v_mul_f32_e32 v11, 0.15915494, v10
	v_fma_f32 v14, v10, 0.15915494, -v11
	v_fract_f32_e32 v11, v11
	v_fmac_f32_e32 v14, 0x31dc9c88, v10
	v_add_f32_e32 v11, v11, v14
	v_sin_f32_e32 v10, v11
	v_cos_f32_e32 v28, v11
	v_mul_f32_e32 v11, v15, v1
	v_mul_f32_e32 v14, 0.15915494, v11
	v_fma_f32 v15, v11, 0.15915494, -v14
	v_fract_f32_e32 v14, v14
	v_fmac_f32_e32 v15, 0x31dc9c88, v11
	v_add_f32_e32 v14, v14, v15
	v_sin_f32_e32 v11, v14
	v_cos_f32_e32 v29, v14
	s_waitcnt vmcnt(0)
	v_pk_mul_f32 v[24:25], v[24:25], v[30:31]
	v_mul_f32_e32 v16, v16, v1
	v_pk_mul_f32 v[14:15], v[10:11], v[24:25]
	v_pk_mul_f32 v[10:11], v[10:11], v[18:19]
	v_pk_fma_f32 v[14:15], v[28:29], v[18:19], v[14:15] neg_lo:[0,0,1] neg_hi:[0,0,1]
	v_mul_f32_e32 v18, 0.15915494, v16
	v_fma_f32 v19, v16, 0.15915494, -v18
	v_pk_fma_f32 v[10:11], v[28:29], v[24:25], v[10:11]
	v_fract_f32_e32 v18, v18
	v_fmac_f32_e32 v19, 0x31dc9c88, v16
	v_pk_mul_f32 v[24:25], v[0:1], v[50:51] op_sel_hi:[0,1]
	v_mul_f32_e32 v17, v17, v1
	v_add_f32_e32 v16, v18, v19
	v_pk_mul_f32 v[20:21], v[20:21], v[24:25]
	v_pk_mul_f32 v[24:25], v[0:1], v[44:45] op_sel_hi:[0,1]
	v_mul_f32_e32 v19, 0.15915494, v17
	v_pk_mul_f32 v[24:25], v[26:27], v[24:25]
	v_fma_f32 v26, v17, 0.15915494, -v19
	v_fract_f32_e32 v19, v19
	v_fmac_f32_e32 v26, 0x31dc9c88, v17
	v_add_f32_e32 v17, v19, v26
	v_sin_f32_e32 v18, v16
	v_sin_f32_e32 v19, v17
	v_cos_f32_e32 v16, v16
	v_cos_f32_e32 v17, v17
	v_cvt_pk_bf16_f32 v14, v14, v15
	v_pk_mul_f32 v[26:27], v[18:19], v[24:25]
	v_pk_mul_f32 v[18:19], v[18:19], v[20:21]
	v_pk_fma_f32 v[26:27], v[16:17], v[20:21], v[26:27] neg_lo:[0,0,1] neg_hi:[0,0,1]
	v_pk_fma_f32 v[16:17], v[16:17], v[24:25], v[18:19]
	v_cvt_pk_bf16_f32 v15, v26, v27
	v_cvt_pk_bf16_f32 v10, v10, v11
	v_cvt_pk_bf16_f32 v11, v16, v17
	global_store_dwordx2 v[48:49], v[14:15], off offset:256
	global_store_dwordx2 v[48:49], v[10:11], off offset:320
	global_load_dwordx4 v[18:21], v116, s[58:59] offset:544
	s_waitcnt vmcnt(0)
; DI unsigned pk2(float a, float b) { f2_t v = {a, b}; bf2_t r = __builtin_convertvector(v, bf2_t); return __builtin_bit_cast(unsigned, r); }
; DI void kv_tile(const Params& p, int mt, int hd, unsigned char* smem) {
;     ...
;     const float posf = (float)p.pos[m];
;     const float* invf = (const float*)(p.ws + WS_CTRL + 256);
; #pragma unroll
;     for (int g = 0; g < 4; ++g) {
;         float o1[4], o2[4];
; #pragma unroll
;         for (int jj = 0; jj < 4; ++jj) {
;             const int i = 8 * g + 4 * h + jj;
;             float sn, cs; sincos_rev(posf * invf[i], sn, cs);
;             const float y1 = x1[4 * g + jj] * rs * p.k_gain[128 + i], y2 = x2[4 * g + jj] * rs * p.k_gain[160 + i];
;             o1[jj] = y1 * cs - y2 * sn; o2[jj] = y2 * cs + y1 * sn;
;         }
;         u32x2 a; a.x = pk2(o1[0], o1[1]); a.y = pk2(o1[2], o1[3]);
;         u32x2 c; c.x = pk2(o2[0], o2[1]); c.y = pk2(o2[2], o2[3]);
;         *(u32x2*)(krow + 128 + 8 * g + 4 * h) = a;
;         *(u32x2*)(krow + 160 + 8 * g + 4 * h) = c;
;     }
	v_pk_mul_f32 v[18:19], v[18:19], v[22:23]
	global_load_dwordx4 v[14:17], v116, s[72:73] offset:288
	global_load_dwordx4 v[22:25], v116, s[58:59] offset:672
	v_pk_mul_f32 v[8:9], v[20:21], v[8:9]
	s_waitcnt vmcnt(1)
	v_mul_f32_e32 v10, v14, v1
	v_mul_f32_e32 v11, 0.15915494, v10
	v_fma_f32 v14, v10, 0.15915494, -v11
	v_fract_f32_e32 v11, v11
	v_fmac_f32_e32 v14, 0x31dc9c88, v10
	v_add_f32_e32 v11, v11, v14
	v_sin_f32_e32 v10, v11
	v_cos_f32_e32 v14, v11
	v_mul_f32_e32 v11, v15, v1
	s_waitcnt vmcnt(0)
	v_pk_mul_f32 v[22:23], v[22:23], v[12:13]
	v_mul_f32_e32 v12, 0.15915494, v11
	v_fma_f32 v13, v11, 0.15915494, -v12
	v_fract_f32_e32 v12, v12
	v_fmac_f32_e32 v13, 0x31dc9c88, v11
	v_add_f32_e32 v12, v12, v13
	v_sin_f32_e32 v11, v12
	v_cos_f32_e32 v15, v12
	v_pk_mul_f32 v[6:7], v[24:25], v[6:7]
	v_pk_mul_f32 v[12:13], v[10:11], v[22:23]
	v_pk_mul_f32 v[10:11], v[10:11], v[18:19]
	v_pk_fma_f32 v[12:13], v[14:15], v[18:19], v[12:13] neg_lo:[0,0,1] neg_hi:[0,0,1]
	v_pk_fma_f32 v[10:11], v[14:15], v[22:23], v[10:11]
	v_mul_f32_e32 v14, v16, v1
	v_mul_f32_e32 v15, 0.15915494, v14
	v_fma_f32 v16, v14, 0.15915494, -v15
	v_fract_f32_e32 v15, v15
	v_fmac_f32_e32 v16, 0x31dc9c88, v14
	v_add_f32_e32 v14, v15, v16
	v_mul_f32_e32 v15, v17, v1
	v_mul_f32_e32 v17, 0.15915494, v15
	v_fma_f32 v18, v15, 0.15915494, -v17
	v_fract_f32_e32 v17, v17
	v_fmac_f32_e32 v18, 0x31dc9c88, v15
	v_add_f32_e32 v15, v17, v18
	v_sin_f32_e32 v16, v14
	v_sin_f32_e32 v17, v15
	v_cos_f32_e32 v14, v14
	v_cos_f32_e32 v15, v15
	v_cvt_pk_bf16_f32 v10, v10, v11
	v_pk_mul_f32 v[18:19], v[16:17], v[6:7]
	s_nop 0
	v_pk_fma_f32 v[18:19], v[14:15], v[8:9], v[18:19] neg_lo:[0,0,1] neg_hi:[0,0,1]
	v_pk_mul_f32 v[8:9], v[16:17], v[8:9]
	s_nop 0
	v_pk_fma_f32 v[6:7], v[14:15], v[6:7], v[8:9]
	v_cvt_pk_bf16_f32 v8, v12, v13
	v_cvt_pk_bf16_f32 v9, v18, v19
	v_cvt_pk_bf16_f32 v11, v6, v7
	global_store_dwordx2 v[48:49], v[8:9], off offset:272
	global_store_dwordx2 v[48:49], v[10:11], off offset:336
	global_load_dwordx4 v[6:9], v116, s[72:73] offset:320
	s_waitcnt vmcnt(0)
	v_mul_f32_e32 v6, v6, v1
	v_mul_f32_e32 v10, 0.15915494, v6
	v_fma_f32 v11, v6, 0.15915494, -v10
	v_fract_f32_e32 v10, v10
	v_fmac_f32_e32 v11, 0x31dc9c88, v6
	v_add_f32_e32 v10, v10, v11
	v_sin_f32_e32 v6, v10
	v_cos_f32_e32 v18, v10
	global_load_dwordx4 v[10:13], v116, s[58:59] offset:576
	global_load_dwordx4 v[14:17], v116, s[58:59] offset:704
	s_waitcnt vmcnt(1)
	v_pk_mul_f32 v[10:11], v[10:11], v[4:5]
	v_mul_f32_e32 v4, v7, v1
	v_mul_f32_e32 v5, 0.15915494, v4
	v_fma_f32 v7, v4, 0.15915494, -v5
	v_fract_f32_e32 v5, v5
	v_fmac_f32_e32 v7, 0x31dc9c88, v4
	v_add_f32_e32 v4, v5, v7
	v_sin_f32_e32 v7, v4
	v_cos_f32_e32 v19, v4
	s_waitcnt vmcnt(0)
	v_pk_mul_f32 v[2:3], v[14:15], v[2:3]
	s_nop 0
	v_pk_mul_f32 v[4:5], v[6:7], v[2:3]
	v_pk_mul_f32 v[6:7], v[6:7], v[10:11]
	v_pk_fma_f32 v[4:5], v[18:19], v[10:11], v[4:5] neg_lo:[0,0,1] neg_hi:[0,0,1]
	v_pk_fma_f32 v[2:3], v[18:19], v[2:3], v[6:7]
	v_mul_f32_e32 v6, v8, v1
	v_mul_f32_e32 v7, 0.15915494, v6
	v_fma_f32 v8, v6, 0.15915494, -v7
	v_fract_f32_e32 v7, v7
	v_fmac_f32_e32 v8, 0x31dc9c88, v6
	v_add_f32_e32 v6, v7, v8
	v_mul_f32_e32 v7, v9, v1
	v_mul_f32_e32 v9, 0.15915494, v7
	v_fma_f32 v10, v7, 0.15915494, -v9
	v_fract_f32_e32 v9, v9
	v_fmac_f32_e32 v10, 0x31dc9c88, v7
	v_add_f32_e32 v7, v9, v10
	v_sin_f32_e32 v8, v6
	v_sin_f32_e32 v9, v7
	v_cos_f32_e32 v6, v6
	v_cos_f32_e32 v7, v7
	v_pk_mul_f32 v[10:11], v[0:1], v[82:83] op_sel_hi:[0,1]
	v_pk_mul_f32 v[10:11], v[12:13], v[10:11] op_sel:[0,1] op_sel_hi:[1,0]
	v_pk_mul_f32 v[12:13], v[0:1], v[76:77] op_sel_hi:[0,1]
	v_pk_mul_f32 v[12:13], v[16:17], v[12:13] op_sel:[0,1] op_sel_hi:[1,0]
	v_cvt_pk_bf16_f32 v4, v4, v5
	v_pk_mul_f32 v[14:15], v[8:9], v[12:13]
	v_pk_mul_f32 v[8:9], v[8:9], v[10:11]
	v_pk_fma_f32 v[14:15], v[6:7], v[10:11], v[14:15] neg_lo:[0,0,1] neg_hi:[0,0,1]
	v_pk_fma_f32 v[6:7], v[6:7], v[12:13], v[8:9]
	v_cvt_pk_bf16_f32 v5, v14, v15
	v_cvt_pk_bf16_f32 v2, v2, v3
	v_cvt_pk_bf16_f32 v3, v6, v7
	global_store_dwordx2 v[48:49], v[4:5], off offset:288
	global_store_dwordx2 v[48:49], v[2:3], off offset:352
	global_load_dwordx4 v[4:7], v116, s[72:73] offset:352
	s_waitcnt vmcnt(0)
	v_mul_f32_e32 v2, v4, v1
	global_load_dwordx4 v[8:11], v116, s[58:59] offset:608
	global_load_dwordx4 v[12:15], v116, s[58:59] offset:736
	v_mul_f32_e32 v3, 0.15915494, v2
	v_fma_f32 v4, v2, 0.15915494, -v3
	v_fract_f32_e32 v3, v3
	v_fmac_f32_e32 v4, 0x31dc9c88, v2
	v_add_f32_e32 v3, v3, v4
	v_sin_f32_e32 v2, v3
	v_cos_f32_e32 v16, v3
	v_mul_f32_e32 v3, v5, v1
	v_mul_f32_e32 v4, 0.15915494, v3
	v_fma_f32 v5, v3, 0.15915494, -v4
	v_fract_f32_e32 v4, v4
	v_fmac_f32_e32 v5, 0x31dc9c88, v3
	v_add_f32_e32 v4, v4, v5
	v_sin_f32_e32 v3, v4
	v_cos_f32_e32 v17, v4
	v_pk_mul_f32 v[4:5], v[0:1], v[74:75] op_sel_hi:[0,1]
	v_mul_f32_e32 v6, v6, v1
	s_waitcnt vmcnt(1)
	v_pk_mul_f32 v[8:9], v[8:9], v[4:5] op_sel:[0,1] op_sel_hi:[1,0]
	v_pk_mul_f32 v[4:5], v[0:1], v[72:73] op_sel_hi:[0,1]
	s_waitcnt vmcnt(0)
	v_pk_mul_f32 v[12:13], v[12:13], v[4:5] op_sel:[0,1] op_sel_hi:[1,0]
	v_mul_f32_e32 v1, v7, v1
	v_pk_mul_f32 v[4:5], v[2:3], v[12:13]
	v_pk_mul_f32 v[2:3], v[2:3], v[8:9]
	v_pk_fma_f32 v[4:5], v[16:17], v[8:9], v[4:5] neg_lo:[0,0,1] neg_hi:[0,0,1]
	v_mul_f32_e32 v8, 0.15915494, v6
	v_fma_f32 v9, v6, 0.15915494, -v8
	v_fract_f32_e32 v8, v8
	v_fmac_f32_e32 v9, 0x31dc9c88, v6
	v_mul_f32_e32 v7, 0.15915494, v1
	v_add_f32_e32 v6, v8, v9
	v_fma_f32 v9, v1, 0.15915494, -v7
	v_fract_f32_e32 v7, v7
	v_fmac_f32_e32 v9, 0x31dc9c88, v1
	v_add_f32_e32 v1, v7, v9
	v_sin_f32_e32 v8, v6
	v_sin_f32_e32 v9, v1
	v_cos_f32_e32 v6, v6
	v_cos_f32_e32 v7, v1
	v_pk_fma_f32 v[2:3], v[16:17], v[12:13], v[2:3]
	v_pk_mul_f32 v[12:13], v[0:1], v[70:71] op_sel_hi:[0,1]
	v_pk_mul_f32 v[0:1], v[0:1], v[68:69] op_sel_hi:[0,1]
	v_pk_mul_f32 v[0:1], v[14:15], v[0:1] op_sel:[0,1] op_sel_hi:[1,0]
	v_pk_mul_f32 v[10:11], v[10:11], v[12:13] op_sel:[0,1] op_sel_hi:[1,0]
	v_pk_mul_f32 v[12:13], v[8:9], v[0:1]
	v_pk_mul_f32 v[8:9], v[8:9], v[10:11]
	v_pk_fma_f32 v[12:13], v[6:7], v[10:11], v[12:13] neg_lo:[0,0,1] neg_hi:[0,0,1]
	v_pk_fma_f32 v[0:1], v[6:7], v[0:1], v[8:9]
	v_cvt_pk_bf16_f32 v4, v4, v5
	v_cvt_pk_bf16_f32 v5, v12, v13
	v_cvt_pk_bf16_f32 v2, v2, v3
	v_cvt_pk_bf16_f32 v3, v0, v1
	global_store_dwordx2 v[48:49], v[4:5], off offset:304
	global_store_dwordx2 v[48:49], v[2:3], off offset:368

; #define MFMA(a, b, c) __builtin_amdgcn_mfma_f32_32x32x16_bf16((a), (b), (c), 0, 0, 0)
; template <int BM, int BN, int BK, int WAVES_M, int WAVES_N, int UNSWAP_FROM>
; DI void gemm_mainloop(const int tid, const bf16_t* __restrict__ A, int lda, const bf16_t* __restrict__ Bt, int ldb, int K, unsigned char* smem,
;                       f32x16 (&acc)[BM / WAVES_M / 32][BN / WAVES_N / 32]) {
;     ...
;     for (int kt = 0; kt < nk; ++kt) {
;         const int buf = kt & 1;
;         if (kt + 1 < nk) G_LOAD(kt + 1);
;         const unsigned char* sa_ = smem + buf * STAGE; const unsigned char* sb_ = sa_ + A_ST;
; #pragma unroll
;         for (int ks = 0; ks < BK / 16; ++ks) {
;             bf16x8 af[WM], bfr[WN];
; #pragma unroll
;             for (int i = 0; i < WM; ++i) af[i] = *(const bf16x8*)(sa_ + (((wm * WM + i) * 32 + r) * LS + ks * 16 + h * 8) * 2);
; #pragma unroll
;             for (int j = 0; j < WN; ++j) bfr[j] = *(const bf16x8*)(sb_ + (((wn * WN + j) * 32 + r) * LS + ks * 16 + h * 8) * 2);
; #pragma unroll
;             for (int i = 0; i < WM; ++i)
; #pragma unroll
;                 for (int j = 0; j < WN; ++j) {
;                     if (j < UNSWAP_FROM) acc[i][j] = MFMA(bfr[j], af[i], acc[i][j]);
;                     else acc[i][j] = MFMA(af[i], bfr[j], acc[i][j]);
;                 }
;         }
;         if (kt + 1 < nk) G_STORE(buf ^ 1);
;         __syncthreads();
.Lq_roll:
	global_load_dwordx4 v[96:99], v[120:121], off offset:192
	global_load_dwordx4 v[100:103], v[122:123], off offset:192
	global_load_dwordx4 v[104:107], v[124:125], off offset:192
	global_load_dwordx4 v[108:111], v[126:127], off offset:192
	global_load_dwordx4 v[112:115], v[128:129], off offset:192
	v_mfma_f32_32x32x16_bf16 v[80:95], v[164:167], v[156:159], v[80:95]
	v_mfma_f32_32x32x16_bf16 v[64:79], v[136:139], v[160:163], v[64:79]
	v_mfma_f32_32x32x16_bf16 v[48:63], v[140:143], v[160:163], v[48:63]
	v_mfma_f32_32x32x16_bf16 v[32:47], v[144:147], v[160:163], v[32:47]
	v_mfma_f32_32x32x16_bf16 v[0:15], v[148:151], v[160:163], v[0:15]
	v_mfma_f32_32x32x16_bf16 v[16:31], v[152:155], v[160:163], v[16:31]
	v_mfma_f32_32x32x16_bf16 v[80:95], v[168:171], v[160:163], v[80:95]
	ds_read_b128 v[136:139], v133 offset:12800
	ds_read_b128 v[140:143], v133 offset:15360
	ds_read_b128 v[144:147], v133 offset:17920
	ds_read_b128 v[148:151], v133 offset:20480
	ds_read_b128 v[152:155], v133 offset:23040
	ds_read_b128 v[156:159], v134
	ds_read_b128 v[160:163], v134 offset:32
	ds_read_b128 v[164:167], v133 offset:10240
	ds_read_b128 v[168:171], v133 offset:10272
	s_waitcnt lgkmcnt(3)
	v_mfma_f32_32x32x16_bf16 v[64:79], v[136:139], v[156:159], v[64:79]
	v_mfma_f32_32x32x16_bf16 v[48:63], v[140:143], v[156:159], v[48:63]
	v_mfma_f32_32x32x16_bf16 v[32:47], v[144:147], v[156:159], v[32:47]
	v_mfma_f32_32x32x16_bf16 v[0:15], v[148:151], v[156:159], v[0:15]
	v_mfma_f32_32x32x16_bf16 v[16:31], v[152:155], v[156:159], v[16:31]
	ds_read_b128 v[136:139], v133 offset:12832
	ds_read_b128 v[140:143], v133 offset:15392
	ds_read_b128 v[144:147], v133 offset:17952
	ds_read_b128 v[148:151], v133 offset:20512
	ds_read_b128 v[152:155], v133 offset:23072
	s_waitcnt vmcnt(4)
	ds_write_b128 v130, v[96:99] offset:25600
	s_waitcnt vmcnt(3)
	ds_write_b128 v131, v[100:103] offset:25600
	s_waitcnt vmcnt(2)
	ds_write_b128 v130, v[104:107] offset:35840
	s_waitcnt vmcnt(1)
	ds_write_b128 v131, v[108:111] offset:35840
	s_waitcnt vmcnt(0)
	ds_write_b128 v132, v[112:115] offset:35840
	s_waitcnt lgkmcnt(0)
	s_barrier
	global_load_dwordx4 v[96:99], v[120:121], off offset:256
	global_load_dwordx4 v[100:103], v[122:123], off offset:256
	global_load_dwordx4 v[104:107], v[124:125], off offset:256
	global_load_dwordx4 v[108:111], v[126:127], off offset:256
	global_load_dwordx4 v[112:115], v[128:129], off offset:256
	v_mfma_f32_32x32x16_bf16 v[80:95], v[164:167], v[156:159], v[80:95]
	v_mfma_f32_32x32x16_bf16 v[64:79], v[136:139], v[160:163], v[64:79]
	v_mfma_f32_32x32x16_bf16 v[48:63], v[140:143], v[160:163], v[48:63]
	v_mfma_f32_32x32x16_bf16 v[32:47], v[144:147], v[160:163], v[32:47]
	v_mfma_f32_32x32x16_bf16 v[0:15], v[148:151], v[160:163], v[0:15]
	v_mfma_f32_32x32x16_bf16 v[16:31], v[152:155], v[160:163], v[16:31]
	v_mfma_f32_32x32x16_bf16 v[80:95], v[168:171], v[160:163], v[80:95]
	ds_read_b128 v[136:139], v133 offset:38400
	ds_read_b128 v[140:143], v133 offset:40960
	ds_read_b128 v[144:147], v133 offset:43520
	ds_read_b128 v[148:151], v133 offset:46080
	ds_read_b128 v[152:155], v133 offset:48640
	ds_read_b128 v[156:159], v134 offset:25600
	ds_read_b128 v[160:163], v134 offset:25632
	ds_read_b128 v[164:167], v133 offset:35840
	ds_read_b128 v[168:171], v133 offset:35872
	s_waitcnt lgkmcnt(3)
	v_mfma_f32_32x32x16_bf16 v[64:79], v[136:139], v[156:159], v[64:79]
	v_mfma_f32_32x32x16_bf16 v[48:63], v[140:143], v[156:159], v[48:63]
	v_mfma_f32_32x32x16_bf16 v[32:47], v[144:147], v[156:159], v[32:47]
	v_mfma_f32_32x32x16_bf16 v[0:15], v[148:151], v[156:159], v[0:15]
	v_mfma_f32_32x32x16_bf16 v[16:31], v[152:155], v[156:159], v[16:31]
	ds_read_b128 v[136:139], v133 offset:38432
	ds_read_b128 v[140:143], v133 offset:40992
	ds_read_b128 v[144:147], v133 offset:43552
	ds_read_b128 v[148:151], v133 offset:46112
	ds_read_b128 v[152:155], v133 offset:48672
	s_waitcnt vmcnt(4)
	ds_write_b128 v130, v[96:99]
	s_waitcnt vmcnt(3)
	ds_write_b128 v131, v[100:103]
	s_waitcnt vmcnt(2)
	ds_write_b128 v130, v[104:107] offset:10240
	s_waitcnt vmcnt(1)
	ds_write_b128 v131, v[108:111] offset:10240
	s_waitcnt vmcnt(0)
	ds_write_b128 v132, v[112:115] offset:10240
	s_waitcnt lgkmcnt(0)
	v_lshl_add_u64 v[120:121], v[120:121], 0, s[100:101]
	v_lshl_add_u64 v[122:123], v[122:123], 0, s[100:101]
	v_lshl_add_u64 v[124:125], v[124:125], 0, s[100:101]
	v_lshl_add_u64 v[126:127], v[126:127], 0, s[100:101]
	v_lshl_add_u64 v[128:129], v[128:129], 0, s[100:101]
	s_barrier
	s_add_i32 s99, s99, -1
	s_cmp_lg_u32 s99, 0
	s_cbranch_scc1 .Lq_roll
; #define MFMA(a, b, c) __builtin_amdgcn_mfma_f32_32x32x16_bf16((a), (b), (c), 0, 0, 0)
; template <int BM, int BN, int BK, int WAVES_M, int WAVES_N, int UNSWAP_FROM>
; DI void gemm_mainloop(const int tid, const bf16_t* __restrict__ A, int lda, const bf16_t* __restrict__ Bt, int ldb, int K, unsigned char* smem,
;                       f32x16 (&acc)[BM / WAVES_M / 32][BN / WAVES_N / 32]) {
;     ...
;     for (int kt = 0; kt < nk; ++kt) {
;         const int buf = kt & 1;
;         if (kt + 1 < nk) G_LOAD(kt + 1);
;         const unsigned char* sa_ = smem + buf * STAGE; const unsigned char* sb_ = sa_ + A_ST;
; #pragma unroll
;         for (int ks = 0; ks < BK / 16; ++ks) {
;             bf16x8 af[WM], bfr[WN];
; #pragma unroll
;             for (int i = 0; i < WM; ++i) af[i] = *(const bf16x8*)(sa_ + (((wm * WM + i) * 32 + r) * LS + ks * 16 + h * 8) * 2);
; #pragma unroll
;             for (int j = 0; j < WN; ++j) bfr[j] = *(const bf16x8*)(sb_ + (((wn * WN + j) * 32 + r) * LS + ks * 16 + h * 8) * 2);
; #pragma unroll
;             for (int i = 0; i < WM; ++i)
; #pragma unroll
;                 for (int j = 0; j < WN; ++j) {
;                     if (j < UNSWAP_FROM) acc[i][j] = MFMA(bfr[j], af[i], acc[i][j]);
;                     else acc[i][j] = MFMA(af[i], bfr[j], acc[i][j]);
;                 }
;         }
;         if (kt + 1 < nk) G_STORE(buf ^ 1);
;         __syncthreads();
; DI void q_tile(const Params& p, int mt, int hd, unsigned char* smem) {
;     ...
;     const int m = mt * 128 + wave * 32 + r;
;     const float rq = rsqrtf(ssq[m] * (1.f / 512.f) + EPS);
	s_mov_b32 s100, 0xfffffd00
	s_mov_b32 s101, -1
	v_lshl_add_u64 v[120:121], v[120:121], 0, s[100:101]
	v_lshl_add_u64 v[122:123], v[122:123], 0, s[100:101]
	v_lshl_add_u64 v[124:125], v[124:125], 0, s[100:101]
	v_lshl_add_u64 v[126:127], v[126:127], 0, s[100:101]
	v_lshl_add_u64 v[128:129], v[128:129], 0, s[100:101]
	global_load_dwordx4 v[96:99], v[120:121], off offset:960
	global_load_dwordx4 v[100:103], v[122:123], off offset:960
	global_load_dwordx4 v[104:107], v[124:125], off offset:960
	global_load_dwordx4 v[108:111], v[126:127], off offset:960
	global_load_dwordx4 v[112:115], v[128:129], off offset:960
	v_mfma_f32_32x32x16_bf16 v[80:95], v[164:167], v[156:159], v[80:95]
	v_mfma_f32_32x32x16_bf16 v[64:79], v[136:139], v[160:163], v[64:79]
	v_mfma_f32_32x32x16_bf16 v[48:63], v[140:143], v[160:163], v[48:63]
	v_mfma_f32_32x32x16_bf16 v[80:95], v[168:171], v[160:163], v[80:95]
	v_mfma_f32_32x32x16_bf16 v[32:47], v[144:147], v[160:163], v[32:47]
	v_mfma_f32_32x32x16_bf16 v[0:15], v[148:151], v[160:163], v[0:15]
	v_mfma_f32_32x32x16_bf16 v[16:31], v[152:155], v[160:163], v[16:31]
	ds_read_b128 v[120:123], v133 offset:12800
	ds_read_b128 v[124:127], v133 offset:15360
	ds_read_b128 v[136:139], v133 offset:17920
	ds_read_b128 v[140:143], v133 offset:20480
	ds_read_b128 v[144:147], v133 offset:23040
	ds_read_b128 v[148:151], v134
	ds_read_b128 v[152:155], v134 offset:32
	ds_read_b128 v[156:159], v133 offset:10240
	ds_read_b128 v[160:163], v133 offset:10272
	s_waitcnt lgkmcnt(3)
	v_mfma_f32_32x32x16_bf16 v[64:79], v[120:123], v[148:151], v[64:79]
	v_mfma_f32_32x32x16_bf16 v[48:63], v[124:127], v[148:151], v[48:63]
	s_waitcnt lgkmcnt(1)
	v_mfma_f32_32x32x16_bf16 v[80:95], v[156:159], v[148:151], v[80:95]
	v_mfma_f32_32x32x16_bf16 v[32:47], v[136:139], v[148:151], v[32:47]
	v_mfma_f32_32x32x16_bf16 v[0:15], v[140:143], v[148:151], v[0:15]
	v_mfma_f32_32x32x16_bf16 v[16:31], v[144:147], v[148:151], v[16:31]
	ds_read_b128 v[120:123], v133 offset:12832
	ds_read_b128 v[124:127], v133 offset:15392
	ds_read_b128 v[136:139], v133 offset:17952
	ds_read_b128 v[140:143], v133 offset:20512
	ds_read_b128 v[144:147], v133 offset:23072
	s_waitcnt vmcnt(4)
	ds_write_b128 v130, v[96:99] offset:25600
	s_waitcnt vmcnt(3)
	ds_write_b128 v131, v[100:103] offset:25600
	s_waitcnt vmcnt(2)
	ds_write_b128 v130, v[104:107] offset:35840
	s_waitcnt vmcnt(1)
	ds_write_b128 v131, v[108:111] offset:35840
	s_waitcnt vmcnt(0)
	ds_write_b128 v132, v[112:115] offset:35840
	s_waitcnt lgkmcnt(0)
	s_barrier
	v_mfma_f32_32x32x16_bf16 v[64:79], v[120:123], v[152:155], v[64:79]
	v_mfma_f32_32x32x16_bf16 v[48:63], v[124:127], v[152:155], v[48:63]
	v_mfma_f32_32x32x16_bf16 v[80:95], v[160:163], v[152:155], v[80:95]
	v_mfma_f32_32x32x16_bf16 v[32:47], v[136:139], v[152:155], v[32:47]
	ds_read_b128 v[96:99], v133 offset:38400
	ds_read_b128 v[100:103], v133 offset:40960
	ds_read_b128 v[104:107], v133 offset:43520
	ds_read_b128 v[108:111], v133 offset:46080
	ds_read_b128 v[112:115], v133 offset:48640
	ds_read_b128 v[120:123], v134 offset:25600
	ds_read_b128 v[124:127], v134 offset:25632
	ds_read_b128 v[128:131], v133 offset:35840
	ds_read_b128 v[134:137], v133 offset:35872
	v_mfma_f32_32x32x16_bf16 v[0:15], v[140:143], v[152:155], v[0:15]
	v_mfma_f32_32x32x16_bf16 v[16:31], v[144:147], v[152:155], v[16:31]
	s_waitcnt lgkmcnt(3)
	v_mfma_f32_32x32x16_bf16 v[64:79], v[96:99], v[120:123], v[64:79]
	v_mfma_f32_32x32x16_bf16 v[48:63], v[100:103], v[120:123], v[48:63]
	s_waitcnt lgkmcnt(1)
	v_mfma_f32_32x32x16_bf16 v[80:95], v[128:131], v[120:123], v[80:95]
	v_mfma_f32_32x32x16_bf16 v[32:47], v[104:107], v[120:123], v[32:47]
	v_mfma_f32_32x32x16_bf16 v[0:15], v[108:111], v[120:123], v[0:15]
	v_mfma_f32_32x32x16_bf16 v[16:31], v[112:115], v[120:123], v[16:31]
	ds_read_b128 v[96:99], v133 offset:38432
	ds_read_b128 v[100:103], v133 offset:40992
	ds_read_b128 v[104:107], v133 offset:43552
	ds_read_b128 v[108:111], v133 offset:46112
	ds_read_b128 v[112:115], v133 offset:48672
	s_waitcnt lgkmcnt(0)
	s_barrier
	v_mfma_f32_32x32x16_bf16 v[64:79], v[96:99], v[124:127], v[64:79]
	v_ashrrev_i32_e32 v96, 1, v116
	v_and_b32_e32 v96, 0xffffffe0, v96
	v_mfma_f32_32x32x16_bf16 v[48:63], v[100:103], v[124:127], v[48:63]
	v_lshl_add_u32 v102, s4, 7, v96
	v_or_b32_e32 v100, v102, v119
	v_ashrrev_i32_e32 v101, 31, v100
	s_movk_i32 s4, 0x1fff
	v_mfma_f32_32x32x16_bf16 v[80:95], v[134:137], v[124:127], v[80:95]
	v_mfma_f32_32x32x16_bf16 v[32:47], v[104:107], v[124:127], v[32:47]
	v_mfma_f32_32x32x16_bf16 v[0:15], v[108:111], v[124:127], v[0:15]
	v_mfma_f32_32x32x16_bf16 v[16:31], v[112:115], v[124:127], v[16:31]
	v_lshlrev_b64 v[124:125], 2, v[100:101]
	v_lshl_add_u64 v[96:97], s[12:13], 0, v[124:125]
	global_load_dword v96, v[96:97], off
	s_waitcnt vmcnt(0)
; DI void q_tile(const Params& p, int mt, int hd, unsigned char* smem) {
;     ...
;     const int m = mt * 128 + wave * 32 + r;
;     const float rq = rsqrtf(ssq[m] * (1.f / 512.f) + EPS);
;     float ss = 0.f;
; #pragma unroll
;     for (int j = 0; j < 6; ++j)
; #pragma unroll
;         for (int e = 0; e < 16; ++e) { const float v = acc[0][j][e] * rq; acc[0][j][e] = v; ss += v * v; }
;     ss += __shfl_xor(ss, 32);
;     const float rs = rsqrtf(ss * (1.f / 192.f) + EPS) * QSCALE;
;     const int bb = m >> 13, s = m & 8191;
;     bf16_t* qrow = Q + ((size_t)(bb * 8 + hd) * SEQ_ + s) * 192;
	v_fmamk_f32 v96, v96, 0x3b000000, v202
	v_cmp_gt_f32_e32 vcc, s53, v96
	v_mul_f32_e32 v97, 0x4b800000, v96
	s_nop 0
	v_cndmask_b32_e32 v96, v96, v97, vcc
	v_rsq_f32_e32 v96, v96
	s_nop 0
	v_mul_f32_e32 v97, 0x45800000, v96
	v_cndmask_b32_e32 v122, v96, v97, vcc
	v_pk_mul_f32 v[98:99], v[28:29], v[122:123] op_sel_hi:[1,0]
	v_ashrrev_i32_e32 v28, 10, v102
	v_and_or_b32 v28, v28, -8, s15
	v_ashrrev_i32_e32 v29, 31, v28
	v_lshlrev_b64 v[28:29], 13, v[28:29]
	v_and_or_b32 v28, v100, s4, v28
	v_readlane_b32 s4, v244, 35
	v_readlane_b32 s5, v244, 36
	v_pk_mul_f32 v[96:97], v[30:31], v[122:123] op_sel_hi:[1,0]
	s_movk_i32 s15, 0x180
	v_mov_b64_e32 v[30:31], s[4:5]
	v_mad_u64_u32 v[100:101], s[4:5], v28, s15, v[30:31]
	v_lshrrev_b32_e32 v28, 3, v116
	v_and_b32_e32 v102, 4, v28
	v_pk_mul_f32 v[114:115], v[80:81], v[122:123] op_sel_hi:[1,0]
	v_mad_i32_i24 v101, v29, s15, v101
	v_pk_mul_f32 v[106:107], v[82:83], v[122:123] op_sel_hi:[1,0]
	v_pk_mul_f32 v[128:129], v[114:115], v[114:115]
	v_lshlrev_b32_e32 v116, 1, v102
	v_pk_mul_f32 v[126:127], v[106:107], v[106:107]
	v_lshl_add_u64 v[80:81], v[100:101], 0, v[116:117]
	v_add_f32_e32 v116, v128, v129
	v_pk_mul_f32 v[120:121], v[84:85], v[122:123] op_sel_hi:[1,0]
	v_add_f32_e32 v116, v126, v116
	v_pk_mul_f32 v[132:133], v[120:121], v[120:121]
	v_add_f32_e32 v116, v127, v116
	v_pk_mul_f32 v[112:113], v[86:87], v[122:123] op_sel_hi:[1,0]
	v_add_f32_e32 v116, v132, v116
	v_pk_mul_f32 v[130:131], v[112:113], v[112:113]
	v_add_f32_e32 v116, v133, v116
	v_pk_mul_f32 v[110:111], v[88:89], v[122:123] op_sel_hi:[1,0]
	v_add_f32_e32 v116, v130, v116
	v_pk_mul_f32 v[136:137], v[110:111], v[110:111]
	v_add_f32_e32 v116, v131, v116
	v_lshlrev_b32_e32 v119, 2, v102
	v_pk_mul_f32 v[102:103], v[90:91], v[122:123] op_sel_hi:[1,0]
	v_add_f32_e32 v116, v136, v116
	v_pk_mul_f32 v[134:135], v[102:103], v[102:103]
	v_add_f32_e32 v116, v137, v116
	v_pk_mul_f32 v[100:101], v[92:93], v[122:123] op_sel_hi:[1,0]
	v_add_f32_e32 v116, v134, v116
	v_pk_mul_f32 v[140:141], v[100:101], v[100:101]
	v_add_f32_e32 v116, v135, v116
	v_pk_mul_f32 v[94:95], v[94:95], v[122:123] op_sel_hi:[1,0]
	v_add_f32_e32 v116, v140, v116
	v_pk_mul_f32 v[138:139], v[94:95], v[94:95]
	v_add_f32_e32 v116, v141, v116
	v_pk_mul_f32 v[92:93], v[64:65], v[122:123] op_sel_hi:[1,0]
	v_add_f32_e32 v116, v138, v116
	v_pk_mul_f32 v[144:145], v[92:93], v[92:93]
	v_add_f32_e32 v116, v139, v116
	v_pk_mul_f32 v[90:91], v[66:67], v[122:123] op_sel_hi:[1,0]
	v_add_f32_e32 v116, v144, v116
	v_pk_mul_f32 v[142:143], v[90:91], v[90:91]
	v_add_f32_e32 v116, v145, v116
	v_pk_mul_f32 v[88:89], v[68:69], v[122:123] op_sel_hi:[1,0]
	v_add_f32_e32 v116, v142, v116
	v_pk_mul_f32 v[148:149], v[88:89], v[88:89]
	v_add_f32_e32 v116, v143, v116
	v_pk_mul_f32 v[86:87], v[70:71], v[122:123] op_sel_hi:[1,0]
	v_add_f32_e32 v116, v148, v116
	v_pk_mul_f32 v[146:147], v[86:87], v[86:87]
	v_add_f32_e32 v116, v149, v116
	v_pk_mul_f32 v[84:85], v[72:73], v[122:123] op_sel_hi:[1,0]
	v_add_f32_e32 v116, v146, v116
	v_pk_mul_f32 v[152:153], v[84:85], v[84:85]
	v_add_f32_e32 v116, v147, v116
	v_pk_mul_f32 v[82:83], v[74:75], v[122:123] op_sel_hi:[1,0]
	v_add_f32_e32 v116, v152, v116
	v_pk_mul_f32 v[150:151], v[82:83], v[82:83]
	v_add_f32_e32 v116, v153, v116
	v_pk_mul_f32 v[76:77], v[76:77], v[122:123] op_sel_hi:[1,0]
	v_add_f32_e32 v116, v150, v116
	v_pk_mul_f32 v[156:157], v[76:77], v[76:77]
	v_add_f32_e32 v116, v151, v116
	v_pk_mul_f32 v[78:79], v[78:79], v[122:123] op_sel_hi:[1,0]
	v_add_f32_e32 v116, v156, v116
	v_pk_mul_f32 v[154:155], v[78:79], v[78:79]
	v_add_f32_e32 v116, v157, v116
	v_pk_mul_f32 v[74:75], v[48:49], v[122:123] op_sel_hi:[1,0]
	v_add_f32_e32 v116, v154, v116
	v_pk_mul_f32 v[160:161], v[74:75], v[74:75]
	v_add_f32_e32 v116, v155, v116
	v_pk_mul_f32 v[72:73], v[50:51], v[122:123] op_sel_hi:[1,0]
	v_add_f32_e32 v116, v160, v116
	global_load_dwordx4 v[28:31], v119, s[56:57]
	v_pk_mul_f32 v[158:159], v[72:73], v[72:73]
	v_add_f32_e32 v116, v161, v116
	v_pk_mul_f32 v[70:71], v[52:53], v[122:123] op_sel_hi:[1,0]
	v_add_f32_e32 v116, v158, v116
	v_pk_mul_f32 v[164:165], v[70:71], v[70:71]
	v_add_f32_e32 v116, v159, v116
	v_pk_mul_f32 v[68:69], v[54:55], v[122:123] op_sel_hi:[1,0]
	v_add_f32_e32 v116, v164, v116
	v_pk_mul_f32 v[162:163], v[68:69], v[68:69]
	v_add_f32_e32 v116, v165, v116
	v_pk_mul_f32 v[66:67], v[56:57], v[122:123] op_sel_hi:[1,0]
	v_add_f32_e32 v116, v162, v116
	v_pk_mul_f32 v[168:169], v[66:67], v[66:67]
	v_add_f32_e32 v116, v163, v116
	v_pk_mul_f32 v[64:65], v[58:59], v[122:123] op_sel_hi:[1,0]
	v_add_f32_e32 v116, v168, v116
	v_pk_mul_f32 v[166:167], v[64:65], v[64:65]
	v_add_f32_e32 v116, v169, v116
	v_pk_mul_f32 v[60:61], v[60:61], v[122:123] op_sel_hi:[1,0]
	v_add_f32_e32 v116, v166, v116
	v_pk_mul_f32 v[172:173], v[60:61], v[60:61]
	v_add_f32_e32 v116, v167, v116
	v_pk_mul_f32 v[62:63], v[62:63], v[122:123] op_sel_hi:[1,0]
	v_add_f32_e32 v116, v172, v116
	v_pk_mul_f32 v[170:171], v[62:63], v[62:63]
	v_add_f32_e32 v116, v173, v116
	v_pk_mul_f32 v[58:59], v[32:33], v[122:123] op_sel_hi:[1,0]
	v_add_f32_e32 v116, v170, v116
	v_pk_mul_f32 v[176:177], v[58:59], v[58:59]
	v_add_f32_e32 v116, v171, v116
	v_pk_mul_f32 v[56:57], v[34:35], v[122:123] op_sel_hi:[1,0]
	v_add_f32_e32 v116, v176, v116
	v_pk_mul_f32 v[174:175], v[56:57], v[56:57]
	v_add_f32_e32 v116, v177, v116
	v_pk_mul_f32 v[54:55], v[36:37], v[122:123] op_sel_hi:[1,0]
	v_add_f32_e32 v116, v174, v116
	v_pk_mul_f32 v[180:181], v[54:55], v[54:55]
	v_add_f32_e32 v116, v175, v116
	v_pk_mul_f32 v[52:53], v[38:39], v[122:123] op_sel_hi:[1,0]
	v_add_f32_e32 v116, v180, v116
	v_pk_mul_f32 v[178:179], v[52:53], v[52:53]
; DI unsigned pk2(float a, float b) { f2_t v = {a, b}; bf2_t r = __builtin_convertvector(v, bf2_t); return __builtin_bit_cast(unsigned, r); }
; DI void q_tile(const Params& p, int mt, int hd, unsigned char* smem) {
;     ...
; #pragma unroll
;     for (int j = 0; j < 6; ++j)
; #pragma unroll
;         for (int e = 0; e < 16; ++e) { const float v = acc[0][j][e] * rq; acc[0][j][e] = v; ss += v * v; }
;     ss += __shfl_xor(ss, 32);
;     const float rs = rsqrtf(ss * (1.f / 192.f) + EPS) * QSCALE;
;     const int bb = m >> 13, s = m & 8191;
;     bf16_t* qrow = Q + ((size_t)(bb * 8 + hd) * SEQ_ + s) * 192;
; #pragma unroll
;     for (int j = 0; j < 4; ++j)
; #pragma unroll
;         for (int g = 0; g < 4; ++g) {
;             const int n = j * 32 + 8 * g + 4 * h;
;             const f32x4 gn = *(const f32x4*)(p.q_gain + n);
;             u32x2 o; o.x = pk2(acc[0][j][4 * g] * rs * gn.x, acc[0][j][4 * g + 1] * rs * gn.y);
;             o.y = pk2(acc[0][j][4 * g + 2] * rs * gn.z, acc[0][j][4 * g + 3] * rs * gn.w);
;             *(u32x2*)(qrow + n) = o;
;         }
	v_add_f32_e32 v116, v181, v116
	v_pk_mul_f32 v[50:51], v[40:41], v[122:123] op_sel_hi:[1,0]
	v_add_f32_e32 v116, v178, v116
	v_pk_mul_f32 v[184:185], v[50:51], v[50:51]
	v_add_f32_e32 v116, v179, v116
	v_pk_mul_f32 v[48:49], v[42:43], v[122:123] op_sel_hi:[1,0]
	v_add_f32_e32 v116, v184, v116
	v_pk_mul_f32 v[182:183], v[48:49], v[48:49]
	v_add_f32_e32 v116, v185, v116
	v_pk_mul_f32 v[44:45], v[44:45], v[122:123] op_sel_hi:[1,0]
	v_add_f32_e32 v116, v182, v116
	v_pk_mul_f32 v[188:189], v[44:45], v[44:45]
	v_add_f32_e32 v116, v183, v116
	v_pk_mul_f32 v[46:47], v[46:47], v[122:123] op_sel_hi:[1,0]
	v_add_f32_e32 v116, v188, v116
	v_pk_mul_f32 v[186:187], v[46:47], v[46:47]
	v_add_f32_e32 v116, v189, v116
	v_pk_mul_f32 v[42:43], v[0:1], v[122:123] op_sel_hi:[1,0]
	v_add_f32_e32 v116, v186, v116
	v_pk_mul_f32 v[190:191], v[42:43], v[42:43]
	v_add_f32_e32 v116, v187, v116
	v_pk_mul_f32 v[36:37], v[2:3], v[122:123] op_sel_hi:[1,0]
	v_add_f32_e32 v116, v190, v116
	v_pk_mul_f32 v[2:3], v[36:37], v[36:37]
	v_add_f32_e32 v116, v191, v116
	v_pk_mul_f32 v[34:35], v[18:19], v[122:123] op_sel_hi:[1,0]
	v_pk_mul_f32 v[18:19], v[22:23], v[122:123] op_sel_hi:[1,0]
	v_pk_mul_f32 v[22:23], v[4:5], v[122:123] op_sel_hi:[1,0]
	v_add_f32_e32 v2, v2, v116
	v_pk_mul_f32 v[214:215], v[22:23], v[22:23]
	v_add_f32_e32 v2, v3, v2
	v_pk_mul_f32 v[32:33], v[6:7], v[122:123] op_sel_hi:[1,0]
	v_add_f32_e32 v2, v214, v2
	v_pk_mul_f32 v[210:211], v[32:33], v[32:33]
	v_add_f32_e32 v2, v215, v2
	v_pk_mul_f32 v[38:39], v[16:17], v[122:123] op_sel_hi:[1,0]
	v_pk_mul_f32 v[16:17], v[8:9], v[122:123] op_sel_hi:[1,0]
	v_add_f32_e32 v2, v210, v2
	v_pk_mul_f32 v[220:221], v[16:17], v[16:17]
	v_add_f32_e32 v2, v211, v2
	v_pk_mul_f32 v[10:11], v[10:11], v[122:123] op_sel_hi:[1,0]
	v_add_f32_e32 v2, v220, v2
	v_pk_mul_f32 v[218:219], v[10:11], v[10:11]
	v_add_f32_e32 v2, v221, v2
	v_pk_mul_f32 v[4:5], v[12:13], v[122:123] op_sel_hi:[1,0]
	v_add_f32_e32 v2, v218, v2
	v_pk_mul_f32 v[12:13], v[4:5], v[4:5]
	v_add_f32_e32 v2, v219, v2
	v_pk_mul_f32 v[0:1], v[14:15], v[122:123] op_sel_hi:[1,0]
	v_add_f32_e32 v2, v12, v2
	v_pk_mul_f32 v[14:15], v[0:1], v[0:1]
	v_add_f32_e32 v2, v13, v2
	v_add_f32_e32 v2, v14, v2
	v_pk_mul_f32 v[208:209], v[38:39], v[38:39]
	v_add_f32_e32 v2, v15, v2
	v_add_f32_e32 v2, v208, v2
	v_lshl_add_u64 v[40:41], s[42:43], 0, v[124:125]
	v_pk_mul_f32 v[124:125], v[34:35], v[34:35]
	v_add_f32_e32 v2, v209, v2
	v_pk_mul_f32 v[20:21], v[20:21], v[122:123] op_sel_hi:[1,0]
	v_add_f32_e32 v2, v124, v2
	v_pk_mul_f32 v[216:217], v[20:21], v[20:21]
	v_add_f32_e32 v2, v125, v2
	v_add_f32_e32 v2, v216, v2
	v_pk_mul_f32 v[212:213], v[18:19], v[18:19]
	v_add_f32_e32 v2, v217, v2
	v_pk_mul_f32 v[8:9], v[24:25], v[122:123] op_sel_hi:[1,0]
	v_add_f32_e32 v2, v212, v2
	v_pk_mul_f32 v[24:25], v[8:9], v[8:9]
	v_add_f32_e32 v2, v213, v2
	v_pk_mul_f32 v[6:7], v[26:27], v[122:123] op_sel_hi:[1,0]
	v_add_f32_e32 v2, v24, v2
	v_pk_mul_f32 v[26:27], v[6:7], v[6:7]
	v_add_f32_e32 v2, v25, v2
	v_add_f32_e32 v2, v26, v2
	v_pk_mul_f32 v[104:105], v[98:99], v[98:99]
	v_add_f32_e32 v2, v27, v2
	v_add_f32_e32 v2, v104, v2
	v_pk_mul_f32 v[108:109], v[96:97], v[96:97]
	v_add_f32_e32 v2, v105, v2
	v_add_f32_e32 v2, v108, v2
	v_add_f32_e32 v2, v109, v2
	ds_bpermute_b32 v3, v241, v2
	s_waitcnt lgkmcnt(0)
	v_add_f32_e32 v2, v2, v3
	v_fmamk_f32 v2, v2, 0x3baaaaab, v202
	v_cmp_gt_f32_e32 vcc, s53, v2
	v_mul_f32_e32 v3, 0x4b800000, v2
	s_nop 0
	v_cndmask_b32_e32 v2, v2, v3, vcc
	v_rsq_f32_e32 v2, v2
	s_nop 0
	v_mul_f32_e32 v3, 0x45800000, v2
	v_cndmask_b32_e32 v2, v2, v3, vcc
	v_mul_f32_e32 v2, 0x3dd53b94, v2
	v_pk_mul_f32 v[12:13], v[114:115], v[2:3] op_sel_hi:[1,0]
	v_pk_mul_f32 v[14:15], v[106:107], v[2:3] op_sel_hi:[1,0]
	s_waitcnt vmcnt(0)
	v_pk_mul_f32 v[12:13], v[28:29], v[12:13]
	v_pk_mul_f32 v[14:15], v[30:31], v[14:15]
	v_cvt_pk_bf16_f32 v12, v12, v13
	v_cvt_pk_bf16_f32 v13, v14, v15
	global_store_dwordx2 v[80:81], v[12:13], off
	global_load_dwordx4 v[228:231], v119, s[56:57] offset:32
	global_load_dwordx4 v[232:235], v119, s[56:57] offset:64
	global_load_dwordx4 v[222:225], v119, s[56:57] offset:96
	v_pk_mul_f32 v[24:25], v[120:121], v[2:3] op_sel_hi:[1,0]
	s_waitcnt vmcnt(2)
	v_pk_mul_f32 v[12:13], v[228:229], v[24:25]
	v_pk_mul_f32 v[24:25], v[112:113], v[2:3] op_sel_hi:[1,0]
	v_cvt_pk_bf16_f32 v12, v12, v13
	v_pk_mul_f32 v[14:15], v[230:231], v[24:25]
	v_pk_mul_f32 v[24:25], v[110:111], v[2:3] op_sel_hi:[1,0]
	v_cvt_pk_bf16_f32 v13, v14, v15
	global_store_dwordx2 v[80:81], v[12:13], off offset:16
	global_load_dwordx4 v[228:231], v119, s[56:57] offset:128
	s_waitcnt vmcnt(3)
	v_pk_mul_f32 v[12:13], v[232:233], v[24:25]
	v_pk_mul_f32 v[24:25], v[102:103], v[2:3] op_sel_hi:[1,0]
	v_cvt_pk_bf16_f32 v12, v12, v13
	v_pk_mul_f32 v[14:15], v[234:235], v[24:25]
	v_pk_mul_f32 v[24:25], v[100:101], v[2:3] op_sel_hi:[1,0]
	v_cvt_pk_bf16_f32 v13, v14, v15
	global_store_dwordx2 v[80:81], v[12:13], off offset:32
	global_load_dwordx4 v[232:235], v119, s[56:57] offset:160
	s_waitcnt vmcnt(4)
	v_pk_mul_f32 v[12:13], v[222:223], v[24:25]
	v_pk_mul_f32 v[24:25], v[94:95], v[2:3] op_sel_hi:[1,0]
	v_cvt_pk_bf16_f32 v12, v12, v13
	v_pk_mul_f32 v[14:15], v[224:225], v[24:25]
	v_pk_mul_f32 v[24:25], v[92:93], v[2:3] op_sel_hi:[1,0]
	v_cvt_pk_bf16_f32 v13, v14, v15
	global_store_dwordx2 v[80:81], v[12:13], off offset:48
	global_load_dwordx4 v[222:225], v119, s[56:57] offset:192
	s_waitcnt vmcnt(4)
	v_pk_mul_f32 v[12:13], v[228:229], v[24:25]
	v_pk_mul_f32 v[24:25], v[90:91], v[2:3] op_sel_hi:[1,0]
	v_cvt_pk_bf16_f32 v12, v12, v13
	v_pk_mul_f32 v[14:15], v[230:231], v[24:25]
	v_pk_mul_f32 v[24:25], v[88:89], v[2:3] op_sel_hi:[1,0]
	v_cvt_pk_bf16_f32 v13, v14, v15
	global_store_dwordx2 v[80:81], v[12:13], off offset:64
	global_load_dwordx4 v[228:231], v119, s[56:57] offset:224
	s_waitcnt vmcnt(4)
; DI unsigned pk2(float a, float b) { f2_t v = {a, b}; bf2_t r = __builtin_convertvector(v, bf2_t); return __builtin_bit_cast(unsigned, r); }
; DI void q_tile(const Params& p, int mt, int hd, unsigned char* smem) {
;     ...
; #pragma unroll
;     for (int j = 0; j < 4; ++j)
; #pragma unroll
;         for (int g = 0; g < 4; ++g) {
;             const int n = j * 32 + 8 * g + 4 * h;
;             const f32x4 gn = *(const f32x4*)(p.q_gain + n);
;             u32x2 o; o.x = pk2(acc[0][j][4 * g] * rs * gn.x, acc[0][j][4 * g + 1] * rs * gn.y);
;             o.y = pk2(acc[0][j][4 * g + 2] * rs * gn.z, acc[0][j][4 * g + 3] * rs * gn.w);
;             *(u32x2*)(qrow + n) = o;
;         }
;     const float posf = (float)p.pos[m];
;     const float* invf = (const float*)(p.ws + WS_CTRL + 256);
; #pragma unroll
;     for (int g = 0; g < 4; ++g) {
;         float o1[4], o2[4];
; #pragma unroll
;         for (int jj = 0; jj < 4; ++jj) {
;             const int i = 8 * g + 4 * h + jj;
;             float sn, cs; sincos_rev(posf * invf[i], sn, cs);
;             const float x1 = acc[0][4][4 * g + jj] * rs * p.q_gain[128 + i], x2 = acc[0][5][4 * g + jj] * rs * p.q_gain[160 + i];
;             o1[jj] = x1 * cs - x2 * sn; o2[jj] = x2 * cs + x1 * sn;
;         }
;         u32x2 a; a.x = pk2(o1[0], o1[1]); a.y = pk2(o1[2], o1[3]);
;         u32x2 c; c.x = pk2(o2[0], o2[1]); c.y = pk2(o2[2], o2[3]);
;         *(u32x2*)(qrow + 128 + 8 * g + 4 * h) = a;
;         *(u32x2*)(qrow + 160 + 8 * g + 4 * h) = c;
;     }
	v_pk_mul_f32 v[12:13], v[232:233], v[24:25]
	v_pk_mul_f32 v[24:25], v[86:87], v[2:3] op_sel_hi:[1,0]
	v_cvt_pk_bf16_f32 v12, v12, v13
	v_pk_mul_f32 v[14:15], v[234:235], v[24:25]
	v_pk_mul_f32 v[24:25], v[84:85], v[2:3] op_sel_hi:[1,0]
	v_cvt_pk_bf16_f32 v13, v14, v15
	global_store_dwordx2 v[80:81], v[12:13], off offset:80
	global_load_dwordx4 v[232:235], v119, s[56:57] offset:256
	s_waitcnt vmcnt(4)
	v_pk_mul_f32 v[12:13], v[222:223], v[24:25]
	v_pk_mul_f32 v[24:25], v[82:83], v[2:3] op_sel_hi:[1,0]
	v_cvt_pk_bf16_f32 v12, v12, v13
	v_pk_mul_f32 v[14:15], v[224:225], v[24:25]
	v_pk_mul_f32 v[24:25], v[76:77], v[2:3] op_sel_hi:[1,0]
	v_cvt_pk_bf16_f32 v13, v14, v15
	global_store_dwordx2 v[80:81], v[12:13], off offset:96
	global_load_dwordx4 v[222:225], v119, s[56:57] offset:288
	s_waitcnt vmcnt(4)
	v_pk_mul_f32 v[12:13], v[228:229], v[24:25]
	v_pk_mul_f32 v[24:25], v[78:79], v[2:3] op_sel_hi:[1,0]
	v_cvt_pk_bf16_f32 v12, v12, v13
	v_pk_mul_f32 v[14:15], v[230:231], v[24:25]
	v_pk_mul_f32 v[24:25], v[74:75], v[2:3] op_sel_hi:[1,0]
	v_cvt_pk_bf16_f32 v13, v14, v15
	global_store_dwordx2 v[80:81], v[12:13], off offset:112
	global_load_dwordx4 v[228:231], v119, s[56:57] offset:320
	s_waitcnt vmcnt(4)
	v_pk_mul_f32 v[12:13], v[232:233], v[24:25]
	v_pk_mul_f32 v[24:25], v[72:73], v[2:3] op_sel_hi:[1,0]
	v_cvt_pk_bf16_f32 v12, v12, v13
	v_pk_mul_f32 v[14:15], v[234:235], v[24:25]
	v_pk_mul_f32 v[24:25], v[70:71], v[2:3] op_sel_hi:[1,0]
	v_cvt_pk_bf16_f32 v13, v14, v15
	global_store_dwordx2 v[80:81], v[12:13], off offset:128
	global_load_dwordx4 v[232:235], v119, s[56:57] offset:352
	s_waitcnt vmcnt(4)
	v_pk_mul_f32 v[12:13], v[222:223], v[24:25]
	v_pk_mul_f32 v[24:25], v[68:69], v[2:3] op_sel_hi:[1,0]
	v_cvt_pk_bf16_f32 v12, v12, v13
	v_pk_mul_f32 v[14:15], v[224:225], v[24:25]
	v_pk_mul_f32 v[24:25], v[66:67], v[2:3] op_sel_hi:[1,0]
	v_cvt_pk_bf16_f32 v13, v14, v15
	global_store_dwordx2 v[80:81], v[12:13], off offset:144
	global_load_dwordx4 v[222:225], v119, s[56:57] offset:384
	s_waitcnt vmcnt(4)
	v_pk_mul_f32 v[12:13], v[228:229], v[24:25]
	v_pk_mul_f32 v[24:25], v[64:65], v[2:3] op_sel_hi:[1,0]
	v_cvt_pk_bf16_f32 v12, v12, v13
	v_pk_mul_f32 v[14:15], v[230:231], v[24:25]
	v_pk_mul_f32 v[24:25], v[60:61], v[2:3] op_sel_hi:[1,0]
	v_cvt_pk_bf16_f32 v13, v14, v15
	global_store_dwordx2 v[80:81], v[12:13], off offset:160
	global_load_dwordx4 v[228:231], v119, s[56:57] offset:416
	s_waitcnt vmcnt(4)
	v_pk_mul_f32 v[12:13], v[232:233], v[24:25]
	v_pk_mul_f32 v[24:25], v[62:63], v[2:3] op_sel_hi:[1,0]
	v_cvt_pk_bf16_f32 v12, v12, v13
	v_pk_mul_f32 v[14:15], v[234:235], v[24:25]
	v_pk_mul_f32 v[24:25], v[58:59], v[2:3] op_sel_hi:[1,0]
	v_cvt_pk_bf16_f32 v13, v14, v15
	global_store_dwordx2 v[80:81], v[12:13], off offset:176
	global_load_dwordx4 v[232:235], v119, s[56:57] offset:448
	s_waitcnt vmcnt(4)
	v_pk_mul_f32 v[12:13], v[222:223], v[24:25]
	v_pk_mul_f32 v[24:25], v[56:57], v[2:3] op_sel_hi:[1,0]
	v_cvt_pk_bf16_f32 v12, v12, v13
	v_pk_mul_f32 v[14:15], v[224:225], v[24:25]
	v_pk_mul_f32 v[24:25], v[54:55], v[2:3] op_sel_hi:[1,0]
	v_cvt_pk_bf16_f32 v13, v14, v15
	global_store_dwordx2 v[80:81], v[12:13], off offset:192
	global_load_dwordx4 v[222:225], v119, s[56:57] offset:480
	s_waitcnt vmcnt(4)
	v_pk_mul_f32 v[12:13], v[228:229], v[24:25]
	v_pk_mul_f32 v[24:25], v[52:53], v[2:3] op_sel_hi:[1,0]
	v_cvt_pk_bf16_f32 v12, v12, v13
	v_pk_mul_f32 v[14:15], v[230:231], v[24:25]
	v_pk_mul_f32 v[24:25], v[50:51], v[2:3] op_sel_hi:[1,0]
	v_cvt_pk_bf16_f32 v13, v14, v15
	global_store_dwordx2 v[80:81], v[12:13], off offset:208
	s_waitcnt vmcnt(3)
	v_pk_mul_f32 v[12:13], v[232:233], v[24:25]
	v_pk_mul_f32 v[24:25], v[48:49], v[2:3] op_sel_hi:[1,0]
	v_cvt_pk_bf16_f32 v12, v12, v13
	v_pk_mul_f32 v[14:15], v[234:235], v[24:25]
	v_pk_mul_f32 v[24:25], v[44:45], v[2:3] op_sel_hi:[1,0]
	v_cvt_pk_bf16_f32 v13, v14, v15
	global_store_dwordx2 v[80:81], v[12:13], off offset:224
	s_waitcnt vmcnt(2)
	v_pk_mul_f32 v[12:13], v[222:223], v[24:25]
	v_pk_mul_f32 v[24:25], v[46:47], v[2:3] op_sel_hi:[1,0]
	v_cvt_pk_bf16_f32 v12, v12, v13
	v_pk_mul_f32 v[14:15], v[224:225], v[24:25]
	s_nop 0
	v_cvt_pk_bf16_f32 v13, v14, v15
	global_store_dwordx2 v[80:81], v[12:13], off offset:240
	global_load_dword v3, v[40:41], off
	global_load_dwordx4 v[24:27], v119, s[72:73] offset:256
	global_load_dwordx4 v[28:31], v119, s[56:57] offset:512
	s_waitcnt vmcnt(2)
	v_cvt_f32_i32_e32 v3, v3
	s_waitcnt vmcnt(1)
	v_mul_f32_e32 v12, v24, v3
	v_mul_f32_e32 v13, 0.15915494, v12
	v_fma_f32 v14, v12, 0.15915494, -v13
	v_fract_f32_e32 v13, v13
	v_fmac_f32_e32 v14, 0x31dc9c88, v12
	v_add_f32_e32 v13, v13, v14
	v_pk_mul_f32 v[14:15], v[42:43], v[2:3] op_sel_hi:[1,0]
	v_sin_f32_e32 v12, v13
	s_waitcnt vmcnt(0)
	v_pk_mul_f32 v[28:29], v[28:29], v[14:15]
	v_pk_mul_f32 v[14:15], v[38:39], v[2:3] op_sel_hi:[1,0]
	global_load_dwordx4 v[38:41], v119, s[56:57] offset:640
	v_cos_f32_e32 v24, v13
	v_mul_f32_e32 v13, v25, v3
	v_pk_mul_f32 v[18:19], v[18:19], v[2:3] op_sel_hi:[1,0]
	v_pk_mul_f32 v[8:9], v[8:9], v[2:3] op_sel_hi:[1,0]
	v_pk_mul_f32 v[10:11], v[10:11], v[2:3] op_sel_hi:[1,0]
	v_pk_mul_f32 v[6:7], v[6:7], v[2:3] op_sel_hi:[1,0]
	v_pk_mul_f32 v[4:5], v[4:5], v[2:3] op_sel_hi:[1,0]
	v_pk_mul_f32 v[0:1], v[0:1], v[2:3] op_sel_hi:[1,0]
	s_waitcnt vmcnt(0)
; DI unsigned pk2(float a, float b) { f2_t v = {a, b}; bf2_t r = __builtin_convertvector(v, bf2_t); return __builtin_bit_cast(unsigned, r); }
; DI void q_tile(const Params& p, int mt, int hd, unsigned char* smem) {
;     ...
;     const float posf = (float)p.pos[m];
;     const float* invf = (const float*)(p.ws + WS_CTRL + 256);
; #pragma unroll
;     for (int g = 0; g < 4; ++g) {
;         float o1[4], o2[4];
; #pragma unroll
;         for (int jj = 0; jj < 4; ++jj) {
;             const int i = 8 * g + 4 * h + jj;
;             float sn, cs; sincos_rev(posf * invf[i], sn, cs);
;             const float x1 = acc[0][4][4 * g + jj] * rs * p.q_gain[128 + i], x2 = acc[0][5][4 * g + jj] * rs * p.q_gain[160 + i];
;             o1[jj] = x1 * cs - x2 * sn; o2[jj] = x2 * cs + x1 * sn;
;         }
;         u32x2 a; a.x = pk2(o1[0], o1[1]); a.y = pk2(o1[2], o1[3]);
;         u32x2 c; c.x = pk2(o2[0], o2[1]); c.y = pk2(o2[2], o2[3]);
;         *(u32x2*)(qrow + 128 + 8 * g + 4 * h) = a;
;         *(u32x2*)(qrow + 160 + 8 * g + 4 * h) = c;
;     }
	v_pk_mul_f32 v[38:39], v[38:39], v[14:15]
	v_mul_f32_e32 v14, 0.15915494, v13
	v_fma_f32 v15, v13, 0.15915494, -v14
	v_fract_f32_e32 v14, v14
	v_fmac_f32_e32 v15, 0x31dc9c88, v13
	v_add_f32_e32 v14, v14, v15
	v_sin_f32_e32 v13, v14
	v_cos_f32_e32 v25, v14
	v_pk_mul_f32 v[14:15], v[12:13], v[38:39]
	s_nop 0
	v_pk_fma_f32 v[14:15], v[24:25], v[28:29], v[14:15] neg_lo:[0,0,1] neg_hi:[0,0,1]
	v_pk_mul_f32 v[24:25], v[24:25], v[38:39]
	v_cvt_pk_bf16_f32 v14, v14, v15
	v_pk_fma_f32 v[12:13], v[12:13], v[28:29], v[24:25]
	v_mul_f32_e32 v24, v26, v3
	v_mul_f32_e32 v25, 0.15915494, v24
	v_fma_f32 v26, v24, 0.15915494, -v25
	v_fract_f32_e32 v25, v25
	v_fmac_f32_e32 v26, 0x31dc9c88, v24
	v_add_f32_e32 v25, v25, v26
	v_sin_f32_e32 v24, v25
	v_cos_f32_e32 v26, v25
	v_mul_f32_e32 v25, v27, v3
	v_pk_mul_f32 v[28:29], v[36:37], v[2:3] op_sel_hi:[1,0]
	v_mul_f32_e32 v27, 0.15915494, v25
	v_pk_mul_f32 v[28:29], v[30:31], v[28:29]
	v_pk_mul_f32 v[30:31], v[34:35], v[2:3] op_sel_hi:[1,0]
	v_fma_f32 v34, v25, 0.15915494, -v27
	v_fract_f32_e32 v27, v27
	v_fmac_f32_e32 v34, 0x31dc9c88, v25
	v_add_f32_e32 v27, v27, v34
	v_sin_f32_e32 v25, v27
	v_cos_f32_e32 v27, v27
	v_pk_mul_f32 v[30:31], v[40:41], v[30:31]
	v_cvt_pk_bf16_f32 v12, v12, v13
	v_pk_mul_f32 v[34:35], v[24:25], v[30:31]
	s_nop 0
	v_pk_fma_f32 v[34:35], v[26:27], v[28:29], v[34:35] neg_lo:[0,0,1] neg_hi:[0,0,1]
	v_pk_mul_f32 v[26:27], v[26:27], v[30:31]
	v_cvt_pk_bf16_f32 v15, v34, v35
	v_pk_fma_f32 v[24:25], v[24:25], v[28:29], v[26:27]
	s_nop 0
	v_cvt_pk_bf16_f32 v13, v24, v25
	global_store_dwordx2 v[80:81], v[14:15], off offset:256
	global_store_dwordx2 v[80:81], v[12:13], off offset:320
	global_load_dwordx4 v[24:27], v119, s[72:73] offset:288
	global_load_dwordx4 v[28:31], v119, s[56:57] offset:544
	s_waitcnt vmcnt(1)
	v_mul_f32_e32 v12, v24, v3
	v_mul_f32_e32 v13, 0.15915494, v12
	v_fma_f32 v14, v12, 0.15915494, -v13
	v_fract_f32_e32 v13, v13
	v_fmac_f32_e32 v14, 0x31dc9c88, v12
	v_add_f32_e32 v13, v13, v14
	v_pk_mul_f32 v[14:15], v[22:23], v[2:3] op_sel_hi:[1,0]
	v_sin_f32_e32 v12, v13
	s_waitcnt vmcnt(0)
	v_pk_mul_f32 v[28:29], v[28:29], v[14:15]
	v_pk_mul_f32 v[14:15], v[20:21], v[2:3] op_sel_hi:[1,0]
	global_load_dwordx4 v[20:23], v119, s[56:57] offset:672
	v_cos_f32_e32 v24, v13
	v_mul_f32_e32 v13, v25, v3
	s_waitcnt vmcnt(0)
	v_pk_mul_f32 v[20:21], v[20:21], v[14:15]
	v_mul_f32_e32 v14, 0.15915494, v13
	v_fma_f32 v15, v13, 0.15915494, -v14
	v_fract_f32_e32 v14, v14
	v_fmac_f32_e32 v15, 0x31dc9c88, v13
	v_add_f32_e32 v14, v14, v15
	v_sin_f32_e32 v13, v14
	v_cos_f32_e32 v25, v14
	v_pk_mul_f32 v[18:19], v[22:23], v[18:19]
	v_pk_mul_f32 v[14:15], v[12:13], v[20:21]
	v_pk_mul_f32 v[20:21], v[24:25], v[20:21]
	v_pk_fma_f32 v[14:15], v[24:25], v[28:29], v[14:15] neg_lo:[0,0,1] neg_hi:[0,0,1]
	v_pk_fma_f32 v[12:13], v[12:13], v[28:29], v[20:21]
	v_mul_f32_e32 v20, v26, v3
	v_mul_f32_e32 v21, 0.15915494, v20
	v_fma_f32 v24, v20, 0.15915494, -v21
	v_fract_f32_e32 v21, v21
	v_fmac_f32_e32 v24, 0x31dc9c88, v20
	v_add_f32_e32 v21, v21, v24
	v_sin_f32_e32 v20, v21
	v_cos_f32_e32 v24, v21
	v_mul_f32_e32 v21, v27, v3
	v_mul_f32_e32 v22, 0.15915494, v21
	v_fma_f32 v23, v21, 0.15915494, -v22
	v_fract_f32_e32 v22, v22
	v_fmac_f32_e32 v23, 0x31dc9c88, v21
	v_add_f32_e32 v22, v22, v23
	v_sin_f32_e32 v21, v22
	v_cos_f32_e32 v25, v22
	v_pk_mul_f32 v[28:29], v[32:33], v[2:3] op_sel_hi:[1,0]
	v_cvt_pk_bf16_f32 v14, v14, v15
	v_pk_mul_f32 v[28:29], v[30:31], v[28:29]
	v_pk_mul_f32 v[22:23], v[20:21], v[18:19]
	v_pk_mul_f32 v[18:19], v[24:25], v[18:19]
	v_pk_fma_f32 v[22:23], v[24:25], v[28:29], v[22:23] neg_lo:[0,0,1] neg_hi:[0,0,1]
	v_pk_fma_f32 v[18:19], v[20:21], v[28:29], v[18:19]
	v_cvt_pk_bf16_f32 v15, v22, v23
	v_cvt_pk_bf16_f32 v12, v12, v13
	v_cvt_pk_bf16_f32 v13, v18, v19
	global_store_dwordx2 v[80:81], v[14:15], off offset:272
	global_store_dwordx2 v[80:81], v[12:13], off offset:336
	global_load_dwordx4 v[12:15], v119, s[72:73] offset:320
	v_pk_mul_f32 v[20:21], v[16:17], v[2:3] op_sel_hi:[1,0]
	s_waitcnt vmcnt(0)
; DI unsigned pk2(float a, float b) { f2_t v = {a, b}; bf2_t r = __builtin_convertvector(v, bf2_t); return __builtin_bit_cast(unsigned, r); }
; DI void q_tile(const Params& p, int mt, int hd, unsigned char* smem) {
;     ...
; #pragma unroll
;     for (int g = 0; g < 4; ++g) {
;         float o1[4], o2[4];
; #pragma unroll
;         for (int jj = 0; jj < 4; ++jj) {
;             const int i = 8 * g + 4 * h + jj;
;             float sn, cs; sincos_rev(posf * invf[i], sn, cs);
;             const float x1 = acc[0][4][4 * g + jj] * rs * p.q_gain[128 + i], x2 = acc[0][5][4 * g + jj] * rs * p.q_gain[160 + i];
;             o1[jj] = x1 * cs - x2 * sn; o2[jj] = x2 * cs + x1 * sn;
;         }
;         u32x2 a; a.x = pk2(o1[0], o1[1]); a.y = pk2(o1[2], o1[3]);
;         u32x2 c; c.x = pk2(o2[0], o2[1]); c.y = pk2(o2[2], o2[3]);
;         *(u32x2*)(qrow + 128 + 8 * g + 4 * h) = a;
;         *(u32x2*)(qrow + 160 + 8 * g + 4 * h) = c;
;     }
	v_mul_f32_e32 v12, v12, v3
	v_mul_f32_e32 v18, 0.15915494, v12
	v_fma_f32 v19, v12, 0.15915494, -v18
	v_fract_f32_e32 v18, v18
	v_fmac_f32_e32 v19, 0x31dc9c88, v12
	v_add_f32_e32 v12, v18, v19
	global_load_dwordx4 v[16:19], v119, s[56:57] offset:576
	v_sin_f32_e32 v24, v12
	v_cos_f32_e32 v26, v12
	v_mul_f32_e32 v12, v13, v3
	v_mul_f32_e32 v13, 0.15915494, v12
	v_mul_f32_e32 v14, v14, v3
	v_mul_f32_e32 v15, v15, v3
	s_waitcnt vmcnt(0)
	v_pk_mul_f32 v[16:17], v[16:17], v[20:21]
	global_load_dwordx4 v[20:23], v119, s[56:57] offset:704
	v_pk_mul_f32 v[10:11], v[18:19], v[10:11]
	s_waitcnt vmcnt(0)
	v_pk_mul_f32 v[8:9], v[20:21], v[8:9]
	v_fma_f32 v20, v12, 0.15915494, -v13
	v_fract_f32_e32 v13, v13
	v_fmac_f32_e32 v20, 0x31dc9c88, v12
	v_add_f32_e32 v12, v13, v20
	v_sin_f32_e32 v25, v12
	v_cos_f32_e32 v27, v12
	v_pk_mul_f32 v[6:7], v[22:23], v[6:7]
	v_pk_mul_f32 v[12:13], v[24:25], v[8:9]
	v_pk_mul_f32 v[8:9], v[26:27], v[8:9]
	v_pk_fma_f32 v[12:13], v[26:27], v[16:17], v[12:13] neg_lo:[0,0,1] neg_hi:[0,0,1]
	v_pk_fma_f32 v[8:9], v[24:25], v[16:17], v[8:9]
	v_mul_f32_e32 v16, 0.15915494, v14
	v_fma_f32 v17, v14, 0.15915494, -v16
	v_fract_f32_e32 v16, v16
	v_fmac_f32_e32 v17, 0x31dc9c88, v14
	v_add_f32_e32 v16, v16, v17
	v_mul_f32_e32 v17, 0.15915494, v15
	v_fma_f32 v18, v15, 0.15915494, -v17
	v_fract_f32_e32 v17, v17
	v_fmac_f32_e32 v18, 0x31dc9c88, v15
	v_add_f32_e32 v17, v17, v18
	v_sin_f32_e32 v14, v16
	v_sin_f32_e32 v15, v17
	v_cos_f32_e32 v16, v16
	v_cos_f32_e32 v17, v17
	v_cvt_pk_bf16_f32 v8, v8, v9
	v_pk_mul_f32 v[18:19], v[14:15], v[6:7]
	v_pk_mul_f32 v[6:7], v[16:17], v[6:7]
	v_pk_fma_f32 v[18:19], v[16:17], v[10:11], v[18:19] neg_lo:[0,0,1] neg_hi:[0,0,1]
	v_pk_fma_f32 v[6:7], v[14:15], v[10:11], v[6:7]
	v_cvt_pk_bf16_f32 v10, v12, v13
	v_cvt_pk_bf16_f32 v11, v18, v19
	v_cvt_pk_bf16_f32 v9, v6, v7
	global_store_dwordx2 v[80:81], v[10:11], off offset:288
	global_store_dwordx2 v[80:81], v[8:9], off offset:352
	global_load_dwordx4 v[6:9], v119, s[72:73] offset:352
	s_waitcnt vmcnt(0)
	v_mul_f32_e32 v6, v6, v3
	v_mul_f32_e32 v10, 0.15915494, v6
	v_fma_f32 v11, v6, 0.15915494, -v10
	v_fract_f32_e32 v10, v10
	v_fmac_f32_e32 v11, 0x31dc9c88, v6
	v_add_f32_e32 v6, v10, v11
	global_load_dwordx4 v[10:13], v119, s[56:57] offset:608
	global_load_dwordx4 v[14:17], v119, s[56:57] offset:736
	v_sin_f32_e32 v18, v6
	v_cos_f32_e32 v20, v6
	v_mul_f32_e32 v6, v7, v3
	v_mul_f32_e32 v7, 0.15915494, v6
	v_mul_f32_e32 v8, v8, v3
	s_waitcnt vmcnt(1)
	v_pk_mul_f32 v[4:5], v[10:11], v[4:5]
	v_pk_mul_f32 v[10:11], v[98:99], v[2:3] op_sel_hi:[1,0]
	v_pk_mul_f32 v[0:1], v[12:13], v[0:1]
	s_waitcnt vmcnt(0)
	v_pk_mul_f32 v[10:11], v[14:15], v[10:11]
	v_fma_f32 v14, v6, 0.15915494, -v7
	v_fract_f32_e32 v7, v7
	v_fmac_f32_e32 v14, 0x31dc9c88, v6
	v_add_f32_e32 v6, v7, v14
	v_sin_f32_e32 v19, v6
	v_cos_f32_e32 v21, v6
	v_pk_mul_f32 v[12:13], v[96:97], v[2:3] op_sel_hi:[1,0]
	v_mul_f32_e32 v2, v9, v3
	v_pk_mul_f32 v[6:7], v[18:19], v[10:11]
	v_pk_mul_f32 v[10:11], v[20:21], v[10:11]
	v_pk_fma_f32 v[6:7], v[20:21], v[4:5], v[6:7] neg_lo:[0,0,1] neg_hi:[0,0,1]
	v_pk_fma_f32 v[4:5], v[18:19], v[4:5], v[10:11]
	v_mul_f32_e32 v10, 0.15915494, v8
	v_mul_f32_e32 v3, 0.15915494, v2
	v_fma_f32 v11, v8, 0.15915494, -v10
	v_fma_f32 v9, v2, 0.15915494, -v3
	v_fract_f32_e32 v10, v10
	v_fmac_f32_e32 v11, 0x31dc9c88, v8
	v_fract_f32_e32 v3, v3
	v_fmac_f32_e32 v9, 0x31dc9c88, v2
	v_add_f32_e32 v10, v10, v11
	v_add_f32_e32 v2, v3, v9
	v_sin_f32_e32 v8, v10
	v_sin_f32_e32 v9, v2
	v_cos_f32_e32 v10, v10
	v_cos_f32_e32 v11, v2
	v_pk_mul_f32 v[12:13], v[16:17], v[12:13]
	v_cvt_pk_bf16_f32 v6, v6, v7
	v_pk_mul_f32 v[2:3], v[8:9], v[12:13]
	s_nop 0
	v_pk_fma_f32 v[2:3], v[10:11], v[0:1], v[2:3] neg_lo:[0,0,1] neg_hi:[0,0,1]
	v_pk_mul_f32 v[10:11], v[10:11], v[12:13]
	v_cvt_pk_bf16_f32 v7, v2, v3
	v_pk_fma_f32 v[0:1], v[8:9], v[0:1], v[10:11]
	v_cvt_pk_bf16_f32 v2, v4, v5
	v_cvt_pk_bf16_f32 v3, v0, v1
	global_store_dwordx2 v[80:81], v[6:7], off offset:304
	global_store_dwordx2 v[80:81], v[2:3], off offset:368
